# A/B: all per-phase s_setprio flips in the five GEMM K-loops deleted (priority stays 0), on top of combined edits
# speedup vs baseline: 1.0172x; 1.0172x over previous
; #define PG8_STAGE(bufoff, gbase, voff) do { _Pragma("unroll") for (int _i = 0; _i < 2; ++_i) \
;         __builtin_amdgcn_global_load_lds((const unsigned*)((const char*)(gbase) + (voff)[_i]), (LAS unsigned*)(lds + (bufoff) + ldsw + _i * 8192), 16, 0, 0); } while (0)
; #define PG8_LDA(dst, b, h) do { _Pragma("unroll") for (int m = 0; m < 4; ++m) _Pragma("unroll") for (int k = 0; k < 2; ++k) dst[m][k] = *(const LAS f16x8*)(lds + PG8_SA(b, h) + aoff + m * 2048 + k * 1024); } while (0)
; #define PG8_LDB(dst, b, h) do { _Pragma("unroll") for (int n = 0; n < 2; ++n) _Pragma("unroll") for (int k = 0; k < 2; ++k) dst[n][k] = *(const LAS f16x8*)(lds + PG8_SB(b, h) + boff + n * 2048 + k * 1024); } while (0)
; #define PG8_MMA(ai, bj, At, Bt) do { __builtin_amdgcn_s_setprio(1); _Pragma("unroll") for (int m = 0; m < 4; ++m) _Pragma("unroll") for (int n = 0; n < 2; ++n) _Pragma("unroll") for (int k = 0; k < 2; ++k) \
;         acc[ai][bj][m][n] = __builtin_amdgcn_mfma_f32_16x16x32_f16(Bt[n][k], At[m][k], acc[ai][bj][m][n], 0, 0, 0); __builtin_amdgcn_s_setprio(0); } while (0)
; #define PG8_WAIT_L(n) asm volatile("s_waitcnt lgkmcnt(" #n ")" ::: "memory")
; #define PG8_BAR __builtin_amdgcn_s_barrier()
; #define PG8_SCHED __builtin_amdgcn_sched_barrier(0)
; template <class Epi>
; __device__ __forceinline__ void gemm_phase(LAS unsigned char* lds, const Gemm g0, const StaticOrder& S, const Epi& E) {
;     ...
;             PG8_LDB(B0, 0, 0); PG8_SCHED; PG8_LDA(At, 0, 0); PG8_STAGE(PG8_SA(1, 1), a1 + hstep, voffA);
;             PG8_WAIT_L(8); PG8_BAR; PG8_WAIT_L(0); PG8_MMA(0, 0, At, B0); PG8_BAR; PG8_SCHED;
;             PG8_LDB(B1, 0, 1); PG8_STAGE(PG8_SB(0, 0), b2, voffB);
;             PG8_BAR; PG8_WAIT_L(0); PG8_MMA(0, 1, At, B1); PG8_BAR;
;             PG8_LDA(At, 0, 1); PG8_STAGE(PG8_SA(0, 0), a2, voffA);
;             PG8_BAR; PG8_WAIT_L(0); PG8_MMA(1, 0, At, B0); PG8_BAR; PG8_SCHED;
.LBB0_198:
	s_add_u32 s52, s0, 0xfff80080
	s_addc_u32 s53, s1, -1
	s_and_b64 s[22:23], s[50:51], exec
	s_cselect_b32 s53, s75, s53
	s_cselect_b32 s52, s80, s52
	s_add_i32 s84, 0, 0x10000
	v_add_u32_e32 v148, s84, v214
	ds_read_b128 v[136:139], v148
	ds_read_b128 v[140:143], v148 offset:1024
	ds_read_b128 v[144:147], v148 offset:2048
	ds_read_b128 v[148:151], v148 offset:3072
	s_and_b64 s[22:23], s[50:51], exec
	s_cselect_b32 s51, s81, s25
	s_cselect_b32 s50, s82, s24
	v_lshl_add_u64 v[160:161], s[0:1], 0, v[184:185]
	s_add_i32 m0, s28, 0xc000
	ds_read_b128 v[152:155], v222
	ds_read_b128 v[156:159], v222 offset:1024
	ds_read_b128 v[186:189], v222 offset:2048
	ds_read_b128 v[190:193], v222 offset:3072
	ds_read_b128 v[194:197], v222 offset:4096
	ds_read_b128 v[198:201], v222 offset:5120
	ds_read_b128 v[202:205], v222 offset:6144
	ds_read_b128 v[206:209], v222 offset:7168
	global_load_lds_dwordx4 v[160:161], off
	v_lshl_add_u64 v[160:161], s[0:1], 0, v[182:183]
	s_add_i32 m0, s28, 0xe000
	s_nop 0
	global_load_lds_dwordx4 v[160:161], off
	s_waitcnt lgkmcnt(8)
	s_barrier
	s_waitcnt lgkmcnt(0)
	s_waitcnt lgkmcnt(0)
	v_mfma_f32_16x16x32_f16 v[126:129], v[136:139], v[152:155], v[126:129]
	v_mfma_f32_16x16x32_f16 v[122:125], v[144:147], v[152:155], v[122:125]
	v_mfma_f32_16x16x32_f16 v[118:121], v[136:139], v[186:189], v[118:121]
	v_mfma_f32_16x16x32_f16 v[110:113], v[144:147], v[186:189], v[110:113]
	v_mfma_f32_16x16x32_f16 v[102:105], v[136:139], v[194:197], v[102:105]
	v_mfma_f32_16x16x32_f16 v[98:101], v[144:147], v[194:197], v[98:101]
	v_mfma_f32_16x16x32_f16 v[86:89], v[136:139], v[202:205], v[86:89]
	v_mfma_f32_16x16x32_f16 v[82:85], v[144:147], v[202:205], v[82:85]
	v_mfma_f32_16x16x32_f16 v[126:129], v[140:143], v[156:159], v[126:129]
	v_mfma_f32_16x16x32_f16 v[122:125], v[148:151], v[156:159], v[122:125]
	v_mfma_f32_16x16x32_f16 v[118:121], v[140:143], v[190:193], v[118:121]
	v_mfma_f32_16x16x32_f16 v[110:113], v[148:151], v[190:193], v[110:113]
	v_mfma_f32_16x16x32_f16 v[102:105], v[140:143], v[198:201], v[102:105]
	v_mfma_f32_16x16x32_f16 v[98:101], v[148:151], v[198:201], v[98:101]
	v_mfma_f32_16x16x32_f16 v[86:89], v[140:143], v[206:209], v[86:89]
	v_mfma_f32_16x16x32_f16 v[82:85], v[148:151], v[206:209], v[82:85]
	s_barrier
	s_add_i32 s85, 0, 0x14000
	v_add_u32_e32 v160, s85, v214
	s_add_i32 s22, s84, s19
	ds_read_b128 v[210:213], v160
	ds_read_b128 v[234:237], v160 offset:1024
	ds_read_b128 v[238:241], v160 offset:2048
	ds_read_b128 v[242:245], v160 offset:3072
	v_lshl_add_u64 v[160:161], s[50:51], 0, v[178:179]
	s_mov_b32 m0, s22
	v_lshl_add_u64 v[162:163], s[50:51], 0, v[174:175]
	global_load_lds_dwordx4 v[160:161], off
	s_add_i32 m0, s22, 0x2000
	s_nop 0
	global_load_lds_dwordx4 v[162:163], off
	s_barrier
	s_waitcnt lgkmcnt(0)
	s_waitcnt lgkmcnt(0)
	v_mfma_f32_16x16x32_f16 v[114:117], v[210:213], v[152:155], v[114:117]
	v_mfma_f32_16x16x32_f16 v[106:109], v[238:241], v[152:155], v[106:109]
	v_mfma_f32_16x16x32_f16 v[94:97], v[210:213], v[186:189], v[94:97]
	v_mfma_f32_16x16x32_f16 v[90:93], v[238:241], v[186:189], v[90:93]
	v_mfma_f32_16x16x32_f16 v[78:81], v[210:213], v[194:197], v[78:81]
	v_mfma_f32_16x16x32_f16 v[74:77], v[238:241], v[194:197], v[74:77]
	v_mfma_f32_16x16x32_f16 v[70:73], v[210:213], v[202:205], v[70:73]
	v_mfma_f32_16x16x32_f16 v[66:69], v[238:241], v[202:205], v[66:69]
	v_mfma_f32_16x16x32_f16 v[114:117], v[234:237], v[156:159], v[114:117]
	v_mfma_f32_16x16x32_f16 v[106:109], v[242:245], v[156:159], v[106:109]
	v_mfma_f32_16x16x32_f16 v[94:97], v[234:237], v[190:193], v[94:97]
	v_mfma_f32_16x16x32_f16 v[90:93], v[242:245], v[190:193], v[90:93]
	v_mfma_f32_16x16x32_f16 v[78:81], v[234:237], v[198:201], v[78:81]
	v_mfma_f32_16x16x32_f16 v[74:77], v[242:245], v[198:201], v[74:77]
	v_mfma_f32_16x16x32_f16 v[70:73], v[234:237], v[206:209], v[70:73]
	v_mfma_f32_16x16x32_f16 v[66:69], v[242:245], v[206:209], v[66:69]
	s_mov_b32 m0, s28
	v_lshl_add_u64 v[164:165], s[52:53], 0, v[180:181]
	s_barrier
	ds_read_b128 v[152:155], v222 offset:16384
	ds_read_b128 v[156:159], v222 offset:17408
	ds_read_b128 v[186:189], v222 offset:18432
	ds_read_b128 v[190:193], v222 offset:19456
	ds_read_b128 v[194:197], v222 offset:20480
	ds_read_b128 v[198:201], v222 offset:21504
	ds_read_b128 v[202:205], v222 offset:22528
	ds_read_b128 v[206:209], v222 offset:23552
	global_load_lds_dwordx4 v[164:165], off
	v_lshl_add_u64 v[170:171], s[52:53], 0, v[176:177]
	s_mov_b32 m0, s29
	s_nop 0
	global_load_lds_dwordx4 v[170:171], off
	s_barrier
	s_waitcnt lgkmcnt(0)
	s_waitcnt lgkmcnt(0)
	v_mfma_f32_16x16x32_f16 v[62:65], v[136:139], v[152:155], v[62:65]
	v_mfma_f32_16x16x32_f16 v[58:61], v[144:147], v[152:155], v[58:61]
	v_mfma_f32_16x16x32_f16 v[54:57], v[136:139], v[186:189], v[54:57]
	v_mfma_f32_16x16x32_f16 v[50:53], v[144:147], v[186:189], v[50:53]
	v_mfma_f32_16x16x32_f16 v[38:41], v[136:139], v[194:197], v[38:41]
	v_mfma_f32_16x16x32_f16 v[30:33], v[144:147], v[194:197], v[30:33]
	v_mfma_f32_16x16x32_f16 v[22:25], v[136:139], v[202:205], v[22:25]
	v_mfma_f32_16x16x32_f16 v[18:21], v[144:147], v[202:205], v[18:21]
	v_mfma_f32_16x16x32_f16 v[62:65], v[140:143], v[156:159], v[62:65]
	v_mfma_f32_16x16x32_f16 v[58:61], v[148:151], v[156:159], v[58:61]
	v_mfma_f32_16x16x32_f16 v[54:57], v[140:143], v[190:193], v[54:57]
	v_mfma_f32_16x16x32_f16 v[50:53], v[148:151], v[190:193], v[50:53]
	v_mfma_f32_16x16x32_f16 v[38:41], v[140:143], v[198:201], v[38:41]
	v_mfma_f32_16x16x32_f16 v[30:33], v[148:151], v[198:201], v[30:33]
	v_mfma_f32_16x16x32_f16 v[22:25], v[140:143], v[206:209], v[22:25]
	v_mfma_f32_16x16x32_f16 v[18:21], v[148:151], v[206:209], v[18:21]
	s_barrier
; #define PG8_STAGE(bufoff, gbase, voff) do { _Pragma("unroll") for (int _i = 0; _i < 2; ++_i) \
;         __builtin_amdgcn_global_load_lds((const unsigned*)((const char*)(gbase) + (voff)[_i]), (LAS unsigned*)(lds + (bufoff) + ldsw + _i * 8192), 16, 0, 0); } while (0)
; #define PG8_LDA(dst, b, h) do { _Pragma("unroll") for (int m = 0; m < 4; ++m) _Pragma("unroll") for (int k = 0; k < 2; ++k) dst[m][k] = *(const LAS f16x8*)(lds + PG8_SA(b, h) + aoff + m * 2048 + k * 1024); } while (0)
; #define PG8_LDB(dst, b, h) do { _Pragma("unroll") for (int n = 0; n < 2; ++n) _Pragma("unroll") for (int k = 0; k < 2; ++k) dst[n][k] = *(const LAS f16x8*)(lds + PG8_SB(b, h) + boff + n * 2048 + k * 1024); } while (0)
; #define PG8_MMA(ai, bj, At, Bt) do { __builtin_amdgcn_s_setprio(1); _Pragma("unroll") for (int m = 0; m < 4; ++m) _Pragma("unroll") for (int n = 0; n < 2; ++n) _Pragma("unroll") for (int k = 0; k < 2; ++k) \
;         acc[ai][bj][m][n] = __builtin_amdgcn_mfma_f32_16x16x32_f16(Bt[n][k], At[m][k], acc[ai][bj][m][n], 0, 0, 0); __builtin_amdgcn_s_setprio(0); } while (0)
; #define PG8_WAIT_V(n) asm volatile("s_waitcnt vmcnt(" #n ")" ::: "memory")
; #define PG8_WAIT_L(n) asm volatile("s_waitcnt lgkmcnt(" #n ")" ::: "memory")
; #define PG8_BAR __builtin_amdgcn_s_barrier()
; #define PG8_SCHED __builtin_amdgcn_sched_barrier(0)
; template <class Epi>
; __device__ __forceinline__ void gemm_phase(LAS unsigned char* lds, const Gemm g0, const StaticOrder& S, const Epi& E) {
;     ...
;             PG8_STAGE(PG8_SB(0, 1), b2 + hstep, voffB);
;             PG8_WAIT_V(6); PG8_BAR; PG8_MMA(1, 1, At, B1); PG8_BAR;
;             PG8_LDB(B0, 1, 0); PG8_SCHED; PG8_LDA(At, 1, 0); PG8_STAGE(PG8_SA(0, 1), a2 + hstep, voffA);
;             PG8_WAIT_L(8); PG8_BAR; PG8_WAIT_L(0); PG8_MMA(0, 0, At, B0); PG8_BAR; PG8_SCHED;
	s_add_u32 s22, s50, 0x80000
	s_addc_u32 s23, s51, 0
	s_add_i32 s84, s85, s19
	v_lshl_add_u64 v[136:137], s[22:23], 0, v[178:179]
	s_mov_b32 m0, s84
	s_nop 0
	global_load_lds_dwordx4 v[136:137], off
	v_lshl_add_u64 v[136:137], s[22:23], 0, v[174:175]
	s_add_i32 m0, s84, 0x2000
	s_nop 0
	global_load_lds_dwordx4 v[136:137], off
	s_waitcnt vmcnt(6)
	s_barrier
	v_mfma_f32_16x16x32_f16 v[46:49], v[210:213], v[152:155], v[46:49]
	v_mfma_f32_16x16x32_f16 v[42:45], v[238:241], v[152:155], v[42:45]
	v_mfma_f32_16x16x32_f16 v[34:37], v[210:213], v[186:189], v[34:37]
	v_mfma_f32_16x16x32_f16 v[26:29], v[238:241], v[186:189], v[26:29]
	v_mfma_f32_16x16x32_f16 v[14:17], v[210:213], v[194:197], v[14:17]
	v_mfma_f32_16x16x32_f16 v[10:13], v[238:241], v[194:197], v[10:13]
	v_mfma_f32_16x16x32_f16 v[6:9], v[210:213], v[202:205], v[6:9]
	v_mfma_f32_16x16x32_f16 v[2:5], v[238:241], v[202:205], v[2:5]
	v_mfma_f32_16x16x32_f16 v[46:49], v[234:237], v[156:159], v[46:49]
	v_mfma_f32_16x16x32_f16 v[42:45], v[242:245], v[156:159], v[42:45]
	v_mfma_f32_16x16x32_f16 v[34:37], v[234:237], v[190:193], v[34:37]
	v_mfma_f32_16x16x32_f16 v[26:29], v[242:245], v[190:193], v[26:29]
	v_mfma_f32_16x16x32_f16 v[14:17], v[234:237], v[198:201], v[14:17]
	v_mfma_f32_16x16x32_f16 v[10:13], v[242:245], v[198:201], v[10:13]
	v_mfma_f32_16x16x32_f16 v[6:9], v[234:237], v[206:209], v[6:9]
	v_mfma_f32_16x16x32_f16 v[2:5], v[242:245], v[206:209], v[2:5]
	s_add_i32 s84, 0, 0x18000
	v_add_u32_e32 v148, s84, v214
	s_barrier
	ds_read_b128 v[136:139], v148
	ds_read_b128 v[140:143], v148 offset:1024
	ds_read_b128 v[144:147], v148 offset:2048
	ds_read_b128 v[148:151], v148 offset:3072
	s_add_u32 s22, s52, 0x80000
	s_addc_u32 s23, s53, 0
	s_mov_b32 m0, s31
	v_lshl_add_u64 v[172:173], s[22:23], 0, v[180:181]
	ds_read_b128 v[152:155], v222 offset:32768
	ds_read_b128 v[156:159], v222 offset:33792
	ds_read_b128 v[186:189], v222 offset:34816
	ds_read_b128 v[190:193], v222 offset:35840
	ds_read_b128 v[194:197], v222 offset:36864
	ds_read_b128 v[198:201], v222 offset:37888
	ds_read_b128 v[202:205], v222 offset:38912
	ds_read_b128 v[206:209], v222 offset:39936
	global_load_lds_dwordx4 v[172:173], off
	v_lshl_add_u64 v[172:173], s[22:23], 0, v[176:177]
	s_mov_b32 m0, s58
	s_nop 0
	global_load_lds_dwordx4 v[172:173], off
	s_waitcnt lgkmcnt(8)
	s_barrier
	s_waitcnt lgkmcnt(0)
	s_waitcnt lgkmcnt(0)
	v_mfma_f32_16x16x32_f16 v[126:129], v[136:139], v[152:155], v[126:129]
	v_mfma_f32_16x16x32_f16 v[122:125], v[144:147], v[152:155], v[122:125]
	v_mfma_f32_16x16x32_f16 v[118:121], v[136:139], v[186:189], v[118:121]
	v_mfma_f32_16x16x32_f16 v[110:113], v[144:147], v[186:189], v[110:113]
	v_mfma_f32_16x16x32_f16 v[102:105], v[136:139], v[194:197], v[102:105]
	v_mfma_f32_16x16x32_f16 v[98:101], v[144:147], v[194:197], v[98:101]
	v_mfma_f32_16x16x32_f16 v[86:89], v[136:139], v[202:205], v[86:89]
	v_mfma_f32_16x16x32_f16 v[82:85], v[144:147], v[202:205], v[82:85]
	v_mfma_f32_16x16x32_f16 v[126:129], v[140:143], v[156:159], v[126:129]
	v_mfma_f32_16x16x32_f16 v[122:125], v[148:151], v[156:159], v[122:125]
	v_mfma_f32_16x16x32_f16 v[118:121], v[140:143], v[190:193], v[118:121]
	v_mfma_f32_16x16x32_f16 v[110:113], v[148:151], v[190:193], v[110:113]
	v_mfma_f32_16x16x32_f16 v[102:105], v[140:143], v[198:201], v[102:105]
	v_mfma_f32_16x16x32_f16 v[98:101], v[148:151], v[198:201], v[98:101]
	v_mfma_f32_16x16x32_f16 v[86:89], v[140:143], v[206:209], v[86:89]
	v_mfma_f32_16x16x32_f16 v[82:85], v[148:151], v[206:209], v[82:85]
	s_barrier
	s_add_i32 s52, 0, 0x1c000
	s_add_i32 s22, s84, s19
	v_add_u32_e32 v172, s52, v214
	v_lshl_add_u64 v[160:161], v[160:161], 0, s[64:65]
	s_mov_b32 m0, s22
	ds_read_b128 v[210:213], v172
	ds_read_b128 v[234:237], v172 offset:1024
	ds_read_b128 v[238:241], v172 offset:2048
	ds_read_b128 v[242:245], v172 offset:3072
	global_load_lds_dwordx4 v[160:161], off
	v_lshl_add_u64 v[160:161], v[162:163], 0, s[64:65]
	s_add_i32 m0, s22, 0x2000
	s_nop 0
	global_load_lds_dwordx4 v[160:161], off
	s_barrier
; #define PG8_STAGE(bufoff, gbase, voff) do { _Pragma("unroll") for (int _i = 0; _i < 2; ++_i) \
;         __builtin_amdgcn_global_load_lds((const unsigned*)((const char*)(gbase) + (voff)[_i]), (LAS unsigned*)(lds + (bufoff) + ldsw + _i * 8192), 16, 0, 0); } while (0)
; #define PG8_LDA(dst, b, h) do { _Pragma("unroll") for (int m = 0; m < 4; ++m) _Pragma("unroll") for (int k = 0; k < 2; ++k) dst[m][k] = *(const LAS f16x8*)(lds + PG8_SA(b, h) + aoff + m * 2048 + k * 1024); } while (0)
; #define PG8_LDB(dst, b, h) do { _Pragma("unroll") for (int n = 0; n < 2; ++n) _Pragma("unroll") for (int k = 0; k < 2; ++k) dst[n][k] = *(const LAS f16x8*)(lds + PG8_SB(b, h) + boff + n * 2048 + k * 1024); } while (0)
; #define PG8_MMA(ai, bj, At, Bt) do { __builtin_amdgcn_s_setprio(1); _Pragma("unroll") for (int m = 0; m < 4; ++m) _Pragma("unroll") for (int n = 0; n < 2; ++n) _Pragma("unroll") for (int k = 0; k < 2; ++k) \
;         acc[ai][bj][m][n] = __builtin_amdgcn_mfma_f32_16x16x32_f16(Bt[n][k], At[m][k], acc[ai][bj][m][n], 0, 0, 0); __builtin_amdgcn_s_setprio(0); } while (0)
; #define PG8_WAIT_V(n) asm volatile("s_waitcnt vmcnt(" #n ")" ::: "memory")
; #define PG8_WAIT_L(n) asm volatile("s_waitcnt lgkmcnt(" #n ")" ::: "memory")
; #define PG8_BAR __builtin_amdgcn_s_barrier()
; #define PG8_SCHED __builtin_amdgcn_sched_barrier(0)
; template <class Epi>
; __device__ __forceinline__ void gemm_phase(LAS unsigned char* lds, const Gemm g0, const StaticOrder& S, const Epi& E) {
;     ...
;             PG8_LDB(B1, 1, 1); PG8_STAGE(PG8_SB(1, 0), b3, voffB);
;             PG8_BAR; PG8_WAIT_L(0); PG8_MMA(0, 1, At, B1); PG8_BAR;
;             PG8_LDA(At, 1, 1); PG8_STAGE(PG8_SA(1, 0), a3, voffA);
;             PG8_BAR; PG8_WAIT_L(0); PG8_MMA(1, 0, At, B0); PG8_BAR; PG8_SCHED;
;             PG8_STAGE(PG8_SB(1, 1), b3 + hstep, voffB);
;             PG8_WAIT_V(6); PG8_BAR; PG8_MMA(1, 1, At, B1); PG8_BAR;
	s_waitcnt lgkmcnt(0)
	s_waitcnt lgkmcnt(0)
	v_mfma_f32_16x16x32_f16 v[114:117], v[210:213], v[152:155], v[114:117]
	v_mfma_f32_16x16x32_f16 v[106:109], v[238:241], v[152:155], v[106:109]
	v_mfma_f32_16x16x32_f16 v[94:97], v[210:213], v[186:189], v[94:97]
	v_mfma_f32_16x16x32_f16 v[90:93], v[238:241], v[186:189], v[90:93]
	v_mfma_f32_16x16x32_f16 v[78:81], v[210:213], v[194:197], v[78:81]
	v_mfma_f32_16x16x32_f16 v[74:77], v[238:241], v[194:197], v[74:77]
	v_mfma_f32_16x16x32_f16 v[70:73], v[210:213], v[202:205], v[70:73]
	v_mfma_f32_16x16x32_f16 v[66:69], v[238:241], v[202:205], v[66:69]
	v_mfma_f32_16x16x32_f16 v[114:117], v[234:237], v[156:159], v[114:117]
	v_mfma_f32_16x16x32_f16 v[106:109], v[242:245], v[156:159], v[106:109]
	v_mfma_f32_16x16x32_f16 v[94:97], v[234:237], v[190:193], v[94:97]
	v_mfma_f32_16x16x32_f16 v[90:93], v[242:245], v[190:193], v[90:93]
	v_mfma_f32_16x16x32_f16 v[78:81], v[234:237], v[198:201], v[78:81]
	v_mfma_f32_16x16x32_f16 v[74:77], v[242:245], v[198:201], v[74:77]
	v_mfma_f32_16x16x32_f16 v[70:73], v[234:237], v[206:209], v[70:73]
	v_mfma_f32_16x16x32_f16 v[66:69], v[242:245], v[206:209], v[66:69]
	s_mov_b32 m0, s59
	v_lshl_add_u64 v[160:161], v[164:165], 0, s[64:65]
	s_barrier
	ds_read_b128 v[152:155], v222 offset:49152
	ds_read_b128 v[156:159], v222 offset:50176
	ds_read_b128 v[186:189], v222 offset:51200
	ds_read_b128 v[190:193], v222 offset:52224
	ds_read_b128 v[194:197], v222 offset:53248
	ds_read_b128 v[198:201], v222 offset:54272
	ds_read_b128 v[202:205], v222 offset:55296
	ds_read_b128 v[206:209], v222 offset:56320
	global_load_lds_dwordx4 v[160:161], off
	v_lshl_add_u64 v[160:161], v[170:171], 0, s[64:65]
	s_mov_b32 m0, s61
	s_nop 0
	global_load_lds_dwordx4 v[160:161], off
	s_barrier
	s_waitcnt lgkmcnt(0)
	s_waitcnt lgkmcnt(0)
	v_mfma_f32_16x16x32_f16 v[62:65], v[136:139], v[152:155], v[62:65]
	v_mfma_f32_16x16x32_f16 v[58:61], v[144:147], v[152:155], v[58:61]
	v_mfma_f32_16x16x32_f16 v[54:57], v[136:139], v[186:189], v[54:57]
	v_mfma_f32_16x16x32_f16 v[50:53], v[144:147], v[186:189], v[50:53]
	v_mfma_f32_16x16x32_f16 v[38:41], v[136:139], v[194:197], v[38:41]
	v_mfma_f32_16x16x32_f16 v[30:33], v[144:147], v[194:197], v[30:33]
	v_mfma_f32_16x16x32_f16 v[22:25], v[136:139], v[202:205], v[22:25]
	v_mfma_f32_16x16x32_f16 v[18:21], v[144:147], v[202:205], v[18:21]
	v_mfma_f32_16x16x32_f16 v[62:65], v[140:143], v[156:159], v[62:65]
	v_mfma_f32_16x16x32_f16 v[58:61], v[148:151], v[156:159], v[58:61]
	v_mfma_f32_16x16x32_f16 v[54:57], v[140:143], v[190:193], v[54:57]
	v_mfma_f32_16x16x32_f16 v[50:53], v[148:151], v[190:193], v[50:53]
	v_mfma_f32_16x16x32_f16 v[38:41], v[140:143], v[198:201], v[38:41]
	v_mfma_f32_16x16x32_f16 v[30:33], v[148:151], v[198:201], v[30:33]
	v_mfma_f32_16x16x32_f16 v[22:25], v[140:143], v[206:209], v[22:25]
	v_mfma_f32_16x16x32_f16 v[18:21], v[148:151], v[206:209], v[18:21]
	s_barrier
	s_add_u32 s22, s50, 0x80080
	s_addc_u32 s23, s51, 0
	s_add_i32 s50, s52, s19
	v_lshl_add_u64 v[136:137], s[22:23], 0, v[178:179]
	s_mov_b32 m0, s50
	s_nop 0
	global_load_lds_dwordx4 v[136:137], off
	v_lshl_add_u64 v[136:137], s[22:23], 0, v[174:175]
	s_add_i32 m0, s50, 0x2000
	s_nop 0
	global_load_lds_dwordx4 v[136:137], off
	s_waitcnt vmcnt(6)
	s_barrier
	v_mfma_f32_16x16x32_f16 v[46:49], v[210:213], v[152:155], v[46:49]
	v_mfma_f32_16x16x32_f16 v[42:45], v[238:241], v[152:155], v[42:45]
	v_mfma_f32_16x16x32_f16 v[34:37], v[210:213], v[186:189], v[34:37]
	v_mfma_f32_16x16x32_f16 v[26:29], v[238:241], v[186:189], v[26:29]
	v_mfma_f32_16x16x32_f16 v[14:17], v[210:213], v[194:197], v[14:17]
	v_mfma_f32_16x16x32_f16 v[10:13], v[238:241], v[194:197], v[10:13]
	v_mfma_f32_16x16x32_f16 v[6:9], v[210:213], v[202:205], v[6:9]
	v_mfma_f32_16x16x32_f16 v[2:5], v[238:241], v[202:205], v[2:5]
	v_mfma_f32_16x16x32_f16 v[46:49], v[234:237], v[156:159], v[46:49]
	v_mfma_f32_16x16x32_f16 v[42:45], v[242:245], v[156:159], v[42:45]
	v_mfma_f32_16x16x32_f16 v[34:37], v[234:237], v[190:193], v[34:37]
	v_mfma_f32_16x16x32_f16 v[26:29], v[242:245], v[190:193], v[26:29]
	v_mfma_f32_16x16x32_f16 v[14:17], v[234:237], v[198:201], v[14:17]
	v_mfma_f32_16x16x32_f16 v[10:13], v[242:245], v[198:201], v[10:13]
	v_mfma_f32_16x16x32_f16 v[6:9], v[234:237], v[206:209], v[6:9]
	v_mfma_f32_16x16x32_f16 v[2:5], v[242:245], v[206:209], v[2:5]
	s_add_i32 s83, s83, 2
	s_add_u32 s24, s24, 0x100
	s_addc_u32 s25, s25, 0
	s_add_u32 s0, s0, 0x100
	s_addc_u32 s1, s1, 0
	s_cmp_gt_u32 s83, 29
	s_barrier
	s_cbranch_scc1 .LBB0_201

; #define PG8_STAGE(bufoff, gbase, voff) do { _Pragma("unroll") for (int _i = 0; _i < 2; ++_i) \
;         __builtin_amdgcn_global_load_lds((const unsigned*)((const char*)(gbase) + (voff)[_i]), (LAS unsigned*)(lds + (bufoff) + ldsw + _i * 8192), 16, 0, 0); } while (0)
; #define PG8_LDA(dst, b, h) do { _Pragma("unroll") for (int m = 0; m < 4; ++m) _Pragma("unroll") for (int k = 0; k < 2; ++k) dst[m][k] = *(const LAS f16x8*)(lds + PG8_SA(b, h) + aoff + m * 2048 + k * 1024); } while (0)
; #define PG8_LDB(dst, b, h) do { _Pragma("unroll") for (int n = 0; n < 2; ++n) _Pragma("unroll") for (int k = 0; k < 2; ++k) dst[n][k] = *(const LAS f16x8*)(lds + PG8_SB(b, h) + boff + n * 2048 + k * 1024); } while (0)
; #define PG8_MMA(ai, bj, At, Bt) do { __builtin_amdgcn_s_setprio(1); _Pragma("unroll") for (int m = 0; m < 4; ++m) _Pragma("unroll") for (int n = 0; n < 2; ++n) _Pragma("unroll") for (int k = 0; k < 2; ++k) \
;         acc[ai][bj][m][n] = __builtin_amdgcn_mfma_f32_16x16x32_f16(Bt[n][k], At[m][k], acc[ai][bj][m][n], 0, 0, 0); __builtin_amdgcn_s_setprio(0); } while (0)
; #define PG8_WAIT_L(n) asm volatile("s_waitcnt lgkmcnt(" #n ")" ::: "memory")
; #define PG8_BAR __builtin_amdgcn_s_barrier()
; #define PG8_SCHED __builtin_amdgcn_sched_barrier(0)
; template <class Epi>
; __device__ __forceinline__ void gemm_phase(LAS unsigned char* lds, const Gemm g0, const StaticOrder& S, const Epi& E) {
;     ...
;             PG8_LDB(B0, 0, 0); PG8_SCHED; PG8_LDA(At, 0, 0); PG8_STAGE(PG8_SA(1, 1), a1 + hstep, voffA);
;             PG8_WAIT_L(8); PG8_BAR; PG8_WAIT_L(0); PG8_MMA(0, 0, At, B0); PG8_BAR; PG8_SCHED;
;             PG8_LDB(B1, 0, 1); PG8_STAGE(PG8_SB(0, 0), b2, voffB);
;             PG8_BAR; PG8_WAIT_L(0); PG8_MMA(0, 1, At, B1); PG8_BAR;
;             PG8_LDA(At, 0, 1); PG8_STAGE(PG8_SA(0, 0), a2, voffA);
;             PG8_BAR; PG8_WAIT_L(0); PG8_MMA(1, 0, At, B0); PG8_BAR; PG8_SCHED;
.LBB0_302:
	s_add_u32 s22, s6, 0xfff80080
	s_addc_u32 s23, s7, -1
	s_add_i32 s59, 0, 0x10000
	v_add_u32_e32 v146, s59, v148
	ds_read_b128 v[142:145], v146
	ds_read_b128 v[152:155], v146 offset:1024
	ds_read_b128 v[156:159], v146 offset:2048
	ds_read_b128 v[174:177], v146 offset:3072
	s_cmp_eq_u32 s58, 28
	s_cselect_b32 s37, s15, s23
	s_cselect_b32 s36, s52, s22
	s_cselect_b32 s35, s13, s53
	s_cselect_b32 s34, s24, s25
	v_lshl_add_u64 v[146:147], s[6:7], 0, v[140:141]
	s_add_i32 m0, s28, 0xc000
	ds_read_b128 v[178:181], v150
	ds_read_b128 v[182:185], v150 offset:1024
	ds_read_b128 v[186:189], v150 offset:2048
	ds_read_b128 v[190:193], v150 offset:3072
	ds_read_b128 v[194:197], v150 offset:4096
	ds_read_b128 v[198:201], v150 offset:5120
	ds_read_b128 v[202:205], v150 offset:6144
	ds_read_b128 v[206:209], v150 offset:7168
	global_load_lds_dwordx4 v[146:147], off
	v_lshl_add_u64 v[146:147], s[6:7], 0, v[138:139]
	s_add_i32 m0, s28, 0xe000
	s_nop 0
	global_load_lds_dwordx4 v[146:147], off
	s_waitcnt lgkmcnt(8)
	s_barrier
	s_waitcnt lgkmcnt(0)
	s_waitcnt lgkmcnt(0)
	v_mfma_f32_16x16x32_f16 v[126:129], v[142:145], v[178:181], v[126:129]
	v_mfma_f32_16x16x32_f16 v[122:125], v[156:159], v[178:181], v[122:125]
	v_mfma_f32_16x16x32_f16 v[110:113], v[142:145], v[186:189], v[110:113]
	v_mfma_f32_16x16x32_f16 v[106:109], v[156:159], v[186:189], v[106:109]
	v_mfma_f32_16x16x32_f16 v[94:97], v[142:145], v[194:197], v[94:97]
	v_mfma_f32_16x16x32_f16 v[90:93], v[156:159], v[194:197], v[90:93]
	v_mfma_f32_16x16x32_f16 v[78:81], v[142:145], v[202:205], v[78:81]
	v_mfma_f32_16x16x32_f16 v[74:77], v[156:159], v[202:205], v[74:77]
	v_mfma_f32_16x16x32_f16 v[126:129], v[152:155], v[182:185], v[126:129]
	v_mfma_f32_16x16x32_f16 v[122:125], v[174:177], v[182:185], v[122:125]
	v_mfma_f32_16x16x32_f16 v[110:113], v[152:155], v[190:193], v[110:113]
	v_mfma_f32_16x16x32_f16 v[106:109], v[174:177], v[190:193], v[106:109]
	v_mfma_f32_16x16x32_f16 v[94:97], v[152:155], v[198:201], v[94:97]
	v_mfma_f32_16x16x32_f16 v[90:93], v[174:177], v[198:201], v[90:93]
	v_mfma_f32_16x16x32_f16 v[78:81], v[152:155], v[206:209], v[78:81]
	v_mfma_f32_16x16x32_f16 v[74:77], v[174:177], v[206:209], v[74:77]
	s_barrier
	s_add_i32 s61, 0, 0x14000
	v_add_u32_e32 v146, s61, v148
	s_add_i32 s22, s59, s19
	ds_read_b128 v[210:213], v146
	ds_read_b128 v[234:237], v146 offset:1024
	ds_read_b128 v[238:241], v146 offset:2048
	ds_read_b128 v[242:245], v146 offset:3072
	v_lshl_add_u64 v[146:147], s[34:35], 0, v[134:135]
	s_mov_b32 m0, s22
	v_lshl_add_u64 v[160:161], s[34:35], 0, v[130:131]
	global_load_lds_dwordx4 v[146:147], off
	s_add_i32 m0, s22, 0x2000
	s_nop 0
	global_load_lds_dwordx4 v[160:161], off
	s_barrier
	s_waitcnt lgkmcnt(0)
	s_waitcnt lgkmcnt(0)
	v_mfma_f32_16x16x32_f16 v[118:121], v[210:213], v[178:181], v[118:121]
	v_mfma_f32_16x16x32_f16 v[114:117], v[238:241], v[178:181], v[114:117]
	v_mfma_f32_16x16x32_f16 v[102:105], v[210:213], v[186:189], v[102:105]
	v_mfma_f32_16x16x32_f16 v[98:101], v[238:241], v[186:189], v[98:101]
	v_mfma_f32_16x16x32_f16 v[86:89], v[210:213], v[194:197], v[86:89]
	v_mfma_f32_16x16x32_f16 v[82:85], v[238:241], v[194:197], v[82:85]
	v_mfma_f32_16x16x32_f16 v[70:73], v[210:213], v[202:205], v[70:73]
	v_mfma_f32_16x16x32_f16 v[66:69], v[238:241], v[202:205], v[66:69]
	v_mfma_f32_16x16x32_f16 v[118:121], v[234:237], v[182:185], v[118:121]
	v_mfma_f32_16x16x32_f16 v[114:117], v[242:245], v[182:185], v[114:117]
	v_mfma_f32_16x16x32_f16 v[102:105], v[234:237], v[190:193], v[102:105]
	v_mfma_f32_16x16x32_f16 v[98:101], v[242:245], v[190:193], v[98:101]
	v_mfma_f32_16x16x32_f16 v[86:89], v[234:237], v[198:201], v[86:89]
	v_mfma_f32_16x16x32_f16 v[82:85], v[242:245], v[198:201], v[82:85]
	v_mfma_f32_16x16x32_f16 v[70:73], v[234:237], v[206:209], v[70:73]
	v_mfma_f32_16x16x32_f16 v[66:69], v[242:245], v[206:209], v[66:69]
	s_mov_b32 m0, s28
	v_lshl_add_u64 v[162:163], s[36:37], 0, v[136:137]
	s_barrier
	ds_read_b128 v[178:181], v150 offset:16384
	ds_read_b128 v[182:185], v150 offset:17408
	ds_read_b128 v[186:189], v150 offset:18432
	ds_read_b128 v[190:193], v150 offset:19456
	ds_read_b128 v[194:197], v150 offset:20480
	ds_read_b128 v[198:201], v150 offset:21504
	ds_read_b128 v[202:205], v150 offset:22528
	ds_read_b128 v[206:209], v150 offset:23552
	global_load_lds_dwordx4 v[162:163], off
	v_lshl_add_u64 v[164:165], s[36:37], 0, v[132:133]
	s_mov_b32 m0, s29
	s_nop 0
	global_load_lds_dwordx4 v[164:165], off
	s_barrier
	s_waitcnt lgkmcnt(0)
	s_waitcnt lgkmcnt(0)
	v_mfma_f32_16x16x32_f16 v[62:65], v[142:145], v[178:181], v[62:65]
	v_mfma_f32_16x16x32_f16 v[58:61], v[156:159], v[178:181], v[58:61]
	v_mfma_f32_16x16x32_f16 v[46:49], v[142:145], v[186:189], v[46:49]
	v_mfma_f32_16x16x32_f16 v[42:45], v[156:159], v[186:189], v[42:45]
	v_mfma_f32_16x16x32_f16 v[30:33], v[142:145], v[194:197], v[30:33]
	v_mfma_f32_16x16x32_f16 v[26:29], v[156:159], v[194:197], v[26:29]
	v_mfma_f32_16x16x32_f16 v[14:17], v[142:145], v[202:205], v[14:17]
	v_mfma_f32_16x16x32_f16 v[10:13], v[156:159], v[202:205], v[10:13]
	v_mfma_f32_16x16x32_f16 v[62:65], v[152:155], v[182:185], v[62:65]
	v_mfma_f32_16x16x32_f16 v[58:61], v[174:177], v[182:185], v[58:61]
	v_mfma_f32_16x16x32_f16 v[46:49], v[152:155], v[190:193], v[46:49]
	v_mfma_f32_16x16x32_f16 v[42:45], v[174:177], v[190:193], v[42:45]
	v_mfma_f32_16x16x32_f16 v[30:33], v[152:155], v[198:201], v[30:33]
	v_mfma_f32_16x16x32_f16 v[26:29], v[174:177], v[198:201], v[26:29]
	v_mfma_f32_16x16x32_f16 v[14:17], v[152:155], v[206:209], v[14:17]
	v_mfma_f32_16x16x32_f16 v[10:13], v[174:177], v[206:209], v[10:13]
	s_barrier
; #define PG8_STAGE(bufoff, gbase, voff) do { _Pragma("unroll") for (int _i = 0; _i < 2; ++_i) \
;         __builtin_amdgcn_global_load_lds((const unsigned*)((const char*)(gbase) + (voff)[_i]), (LAS unsigned*)(lds + (bufoff) + ldsw + _i * 8192), 16, 0, 0); } while (0)
; #define PG8_LDA(dst, b, h) do { _Pragma("unroll") for (int m = 0; m < 4; ++m) _Pragma("unroll") for (int k = 0; k < 2; ++k) dst[m][k] = *(const LAS f16x8*)(lds + PG8_SA(b, h) + aoff + m * 2048 + k * 1024); } while (0)
; #define PG8_LDB(dst, b, h) do { _Pragma("unroll") for (int n = 0; n < 2; ++n) _Pragma("unroll") for (int k = 0; k < 2; ++k) dst[n][k] = *(const LAS f16x8*)(lds + PG8_SB(b, h) + boff + n * 2048 + k * 1024); } while (0)
; #define PG8_MMA(ai, bj, At, Bt) do { __builtin_amdgcn_s_setprio(1); _Pragma("unroll") for (int m = 0; m < 4; ++m) _Pragma("unroll") for (int n = 0; n < 2; ++n) _Pragma("unroll") for (int k = 0; k < 2; ++k) \
;         acc[ai][bj][m][n] = __builtin_amdgcn_mfma_f32_16x16x32_f16(Bt[n][k], At[m][k], acc[ai][bj][m][n], 0, 0, 0); __builtin_amdgcn_s_setprio(0); } while (0)
; #define PG8_WAIT_V(n) asm volatile("s_waitcnt vmcnt(" #n ")" ::: "memory")
; #define PG8_WAIT_L(n) asm volatile("s_waitcnt lgkmcnt(" #n ")" ::: "memory")
; #define PG8_BAR __builtin_amdgcn_s_barrier()
; #define PG8_SCHED __builtin_amdgcn_sched_barrier(0)
; template <class Epi>
; __device__ __forceinline__ void gemm_phase(LAS unsigned char* lds, const Gemm g0, const StaticOrder& S, const Epi& E) {
;     ...
;             PG8_STAGE(PG8_SB(0, 1), b2 + hstep, voffB);
;             PG8_WAIT_V(6); PG8_BAR; PG8_MMA(1, 1, At, B1); PG8_BAR;
;             PG8_LDB(B0, 1, 0); PG8_SCHED; PG8_LDA(At, 1, 0); PG8_STAGE(PG8_SA(0, 1), a2 + hstep, voffA);
;             PG8_WAIT_L(8); PG8_BAR; PG8_WAIT_L(0); PG8_MMA(0, 0, At, B0); PG8_BAR; PG8_SCHED;
;             PG8_LDB(B1, 1, 1); PG8_STAGE(PG8_SB(1, 0), b3, voffB);
;             PG8_BAR; PG8_WAIT_L(0); PG8_MMA(0, 1, At, B1); PG8_BAR;
	s_add_u32 s22, s34, 0x80000
	s_addc_u32 s23, s35, 0
	s_add_i32 s59, s61, s19
	v_lshl_add_u64 v[142:143], s[22:23], 0, v[134:135]
	s_mov_b32 m0, s59
	s_nop 0
	global_load_lds_dwordx4 v[142:143], off
	v_lshl_add_u64 v[142:143], s[22:23], 0, v[130:131]
	s_add_i32 m0, s59, 0x2000
	s_nop 0
	global_load_lds_dwordx4 v[142:143], off
	s_waitcnt vmcnt(6)
	s_barrier
	v_mfma_f32_16x16x32_f16 v[54:57], v[210:213], v[178:181], v[54:57]
	v_mfma_f32_16x16x32_f16 v[50:53], v[238:241], v[178:181], v[50:53]
	v_mfma_f32_16x16x32_f16 v[38:41], v[210:213], v[186:189], v[38:41]
	v_mfma_f32_16x16x32_f16 v[34:37], v[238:241], v[186:189], v[34:37]
	v_mfma_f32_16x16x32_f16 v[22:25], v[210:213], v[194:197], v[22:25]
	v_mfma_f32_16x16x32_f16 v[18:21], v[238:241], v[194:197], v[18:21]
	v_mfma_f32_16x16x32_f16 v[6:9], v[210:213], v[202:205], v[6:9]
	v_mfma_f32_16x16x32_f16 v[2:5], v[238:241], v[202:205], v[2:5]
	v_mfma_f32_16x16x32_f16 v[54:57], v[234:237], v[182:185], v[54:57]
	v_mfma_f32_16x16x32_f16 v[50:53], v[242:245], v[182:185], v[50:53]
	v_mfma_f32_16x16x32_f16 v[38:41], v[234:237], v[190:193], v[38:41]
	v_mfma_f32_16x16x32_f16 v[34:37], v[242:245], v[190:193], v[34:37]
	v_mfma_f32_16x16x32_f16 v[22:25], v[234:237], v[198:201], v[22:25]
	v_mfma_f32_16x16x32_f16 v[18:21], v[242:245], v[198:201], v[18:21]
	v_mfma_f32_16x16x32_f16 v[6:9], v[234:237], v[206:209], v[6:9]
	v_mfma_f32_16x16x32_f16 v[2:5], v[242:245], v[206:209], v[2:5]
	s_add_i32 s59, 0, 0x18000
	v_add_u32_e32 v151, s59, v148
	s_barrier
	ds_read_b128 v[142:145], v151
	ds_read_b128 v[152:155], v151 offset:1024
	ds_read_b128 v[156:159], v151 offset:2048
	ds_read_b128 v[174:177], v151 offset:3072
	s_add_u32 s22, s36, 0x80000
	s_addc_u32 s23, s37, 0
	s_mov_b32 m0, s31
	v_lshl_add_u64 v[170:171], s[22:23], 0, v[136:137]
	ds_read_b128 v[178:181], v150 offset:32768
	ds_read_b128 v[182:185], v150 offset:33792
	ds_read_b128 v[186:189], v150 offset:34816
	ds_read_b128 v[190:193], v150 offset:35840
	ds_read_b128 v[194:197], v150 offset:36864
	ds_read_b128 v[198:201], v150 offset:37888
	ds_read_b128 v[202:205], v150 offset:38912
	ds_read_b128 v[206:209], v150 offset:39936
	global_load_lds_dwordx4 v[170:171], off
	v_lshl_add_u64 v[170:171], s[22:23], 0, v[132:133]
	s_mov_b32 m0, s38
	s_nop 0
	global_load_lds_dwordx4 v[170:171], off
	s_waitcnt lgkmcnt(8)
	s_barrier
	s_waitcnt lgkmcnt(0)
	s_waitcnt lgkmcnt(0)
	v_mfma_f32_16x16x32_f16 v[126:129], v[142:145], v[178:181], v[126:129]
	v_mfma_f32_16x16x32_f16 v[122:125], v[156:159], v[178:181], v[122:125]
	v_mfma_f32_16x16x32_f16 v[110:113], v[142:145], v[186:189], v[110:113]
	v_mfma_f32_16x16x32_f16 v[106:109], v[156:159], v[186:189], v[106:109]
	v_mfma_f32_16x16x32_f16 v[94:97], v[142:145], v[194:197], v[94:97]
	v_mfma_f32_16x16x32_f16 v[90:93], v[156:159], v[194:197], v[90:93]
	v_mfma_f32_16x16x32_f16 v[78:81], v[142:145], v[202:205], v[78:81]
	v_mfma_f32_16x16x32_f16 v[74:77], v[156:159], v[202:205], v[74:77]
	v_mfma_f32_16x16x32_f16 v[126:129], v[152:155], v[182:185], v[126:129]
	v_mfma_f32_16x16x32_f16 v[122:125], v[174:177], v[182:185], v[122:125]
	v_mfma_f32_16x16x32_f16 v[110:113], v[152:155], v[190:193], v[110:113]
	v_mfma_f32_16x16x32_f16 v[106:109], v[174:177], v[190:193], v[106:109]
	v_mfma_f32_16x16x32_f16 v[94:97], v[152:155], v[198:201], v[94:97]
	v_mfma_f32_16x16x32_f16 v[90:93], v[174:177], v[198:201], v[90:93]
	v_mfma_f32_16x16x32_f16 v[78:81], v[152:155], v[206:209], v[78:81]
	v_mfma_f32_16x16x32_f16 v[74:77], v[174:177], v[206:209], v[74:77]
	s_barrier
	s_add_i32 s36, 0, 0x1c000
	s_add_i32 s22, s59, s19
	v_add_u32_e32 v151, s36, v148
	v_lshl_add_u64 v[146:147], v[146:147], 0, s[64:65]
	s_mov_b32 m0, s22
	ds_read_b128 v[210:213], v151
	ds_read_b128 v[234:237], v151 offset:1024
	ds_read_b128 v[238:241], v151 offset:2048
	ds_read_b128 v[242:245], v151 offset:3072
	global_load_lds_dwordx4 v[146:147], off
	v_lshl_add_u64 v[146:147], v[160:161], 0, s[64:65]
	s_add_i32 m0, s22, 0x2000
	s_nop 0
	global_load_lds_dwordx4 v[146:147], off
	s_barrier
	s_waitcnt lgkmcnt(0)
	s_waitcnt lgkmcnt(0)
	v_mfma_f32_16x16x32_f16 v[118:121], v[210:213], v[178:181], v[118:121]
	v_mfma_f32_16x16x32_f16 v[114:117], v[238:241], v[178:181], v[114:117]
	v_mfma_f32_16x16x32_f16 v[102:105], v[210:213], v[186:189], v[102:105]
	v_mfma_f32_16x16x32_f16 v[98:101], v[238:241], v[186:189], v[98:101]
	v_mfma_f32_16x16x32_f16 v[86:89], v[210:213], v[194:197], v[86:89]
	v_mfma_f32_16x16x32_f16 v[82:85], v[238:241], v[194:197], v[82:85]
	v_mfma_f32_16x16x32_f16 v[70:73], v[210:213], v[202:205], v[70:73]
	v_mfma_f32_16x16x32_f16 v[66:69], v[238:241], v[202:205], v[66:69]
	v_mfma_f32_16x16x32_f16 v[118:121], v[234:237], v[182:185], v[118:121]
	v_mfma_f32_16x16x32_f16 v[114:117], v[242:245], v[182:185], v[114:117]
	v_mfma_f32_16x16x32_f16 v[102:105], v[234:237], v[190:193], v[102:105]
	v_mfma_f32_16x16x32_f16 v[98:101], v[242:245], v[190:193], v[98:101]
	v_mfma_f32_16x16x32_f16 v[86:89], v[234:237], v[198:201], v[86:89]
	v_mfma_f32_16x16x32_f16 v[82:85], v[242:245], v[198:201], v[82:85]
	v_mfma_f32_16x16x32_f16 v[70:73], v[234:237], v[206:209], v[70:73]
	v_mfma_f32_16x16x32_f16 v[66:69], v[242:245], v[206:209], v[66:69]
	s_mov_b32 m0, s39
	v_lshl_add_u64 v[146:147], v[162:163], 0, s[64:65]
	s_barrier
; __device__ __forceinline__ float gelu_tanh(float x) { const float y = 1.5957691216057308f * (x + 0.044715f * x * x * x); return x * fast_rcp(1.0f + __expf(-y)); }
; #define PG8_STAGE(bufoff, gbase, voff) do { _Pragma("unroll") for (int _i = 0; _i < 2; ++_i) \
;         __builtin_amdgcn_global_load_lds((const unsigned*)((const char*)(gbase) + (voff)[_i]), (LAS unsigned*)(lds + (bufoff) + ldsw + _i * 8192), 16, 0, 0); } while (0)
; #define PG8_LDA(dst, b, h) do { _Pragma("unroll") for (int m = 0; m < 4; ++m) _Pragma("unroll") for (int k = 0; k < 2; ++k) dst[m][k] = *(const LAS f16x8*)(lds + PG8_SA(b, h) + aoff + m * 2048 + k * 1024); } while (0)
; #define PG8_MMA(ai, bj, At, Bt) do { __builtin_amdgcn_s_setprio(1); _Pragma("unroll") for (int m = 0; m < 4; ++m) _Pragma("unroll") for (int n = 0; n < 2; ++n) _Pragma("unroll") for (int k = 0; k < 2; ++k) \
;         acc[ai][bj][m][n] = __builtin_amdgcn_mfma_f32_16x16x32_f16(Bt[n][k], At[m][k], acc[ai][bj][m][n], 0, 0, 0); __builtin_amdgcn_s_setprio(0); } while (0)
; #define PG8_WAIT_V(n) asm volatile("s_waitcnt vmcnt(" #n ")" ::: "memory")
; #define PG8_WAIT_L(n) asm volatile("s_waitcnt lgkmcnt(" #n ")" ::: "memory")
; #define PG8_BAR __builtin_amdgcn_s_barrier()
; #define PG8_SCHED __builtin_amdgcn_sched_barrier(0)
;     __device__ __forceinline__ void operator()(f32x4 (&acc)[2][2][4][2], const Unit& u, int wr, int wc, int fr, int fq) const {
;     ...
;                 for (int bj = 0; bj < 2; ++bj) { f32x4 v0 = acc[ai][bj][m][0], v1 = acc[ai][bj][m][1];
;                     if (isy) {
; #pragma unroll
;                         for (int j = 0; j < 4; ++j) { v0[j] = gelu_tanh(v0[j]); v1[j] = gelu_tanh(v1[j]); } }
; template <class Epi>
; __device__ __forceinline__ void gemm_phase(LAS unsigned char* lds, const Gemm g0, const StaticOrder& S, const Epi& E) {
;     ...
;             PG8_LDA(At, 1, 1); PG8_STAGE(PG8_SA(1, 0), a3, voffA);
;             PG8_BAR; PG8_WAIT_L(0); PG8_MMA(1, 0, At, B0); PG8_BAR; PG8_SCHED;
;             PG8_STAGE(PG8_SB(1, 1), b3 + hstep, voffB);
;             PG8_WAIT_V(6); PG8_BAR; PG8_MMA(1, 1, At, B1); PG8_BAR;
	ds_read_b128 v[178:181], v150 offset:49152
	ds_read_b128 v[182:185], v150 offset:50176
	ds_read_b128 v[186:189], v150 offset:51200
	ds_read_b128 v[190:193], v150 offset:52224
	ds_read_b128 v[194:197], v150 offset:53248
	ds_read_b128 v[198:201], v150 offset:54272
	ds_read_b128 v[202:205], v150 offset:55296
	ds_read_b128 v[206:209], v150 offset:56320
	global_load_lds_dwordx4 v[146:147], off
	v_lshl_add_u64 v[146:147], v[164:165], 0, s[64:65]
	s_mov_b32 m0, s48
	s_nop 0
	global_load_lds_dwordx4 v[146:147], off
	s_barrier
	s_waitcnt lgkmcnt(0)
	s_waitcnt lgkmcnt(0)
	v_mfma_f32_16x16x32_f16 v[62:65], v[142:145], v[178:181], v[62:65]
	v_mfma_f32_16x16x32_f16 v[58:61], v[156:159], v[178:181], v[58:61]
	v_mfma_f32_16x16x32_f16 v[46:49], v[142:145], v[186:189], v[46:49]
	v_mfma_f32_16x16x32_f16 v[42:45], v[156:159], v[186:189], v[42:45]
	v_mfma_f32_16x16x32_f16 v[30:33], v[142:145], v[194:197], v[30:33]
	v_mfma_f32_16x16x32_f16 v[26:29], v[156:159], v[194:197], v[26:29]
	v_mfma_f32_16x16x32_f16 v[14:17], v[142:145], v[202:205], v[14:17]
	v_mfma_f32_16x16x32_f16 v[10:13], v[156:159], v[202:205], v[10:13]
	v_mfma_f32_16x16x32_f16 v[62:65], v[152:155], v[182:185], v[62:65]
	v_mfma_f32_16x16x32_f16 v[58:61], v[174:177], v[182:185], v[58:61]
	v_mfma_f32_16x16x32_f16 v[46:49], v[152:155], v[190:193], v[46:49]
	v_mfma_f32_16x16x32_f16 v[42:45], v[174:177], v[190:193], v[42:45]
	v_mfma_f32_16x16x32_f16 v[30:33], v[152:155], v[198:201], v[30:33]
	v_mfma_f32_16x16x32_f16 v[26:29], v[174:177], v[198:201], v[26:29]
	v_mfma_f32_16x16x32_f16 v[14:17], v[152:155], v[206:209], v[14:17]
	v_mfma_f32_16x16x32_f16 v[10:13], v[174:177], v[206:209], v[10:13]
	s_barrier
	s_add_u32 s22, s34, 0x80080
	s_addc_u32 s23, s35, 0
	s_add_i32 s34, s36, s19
	v_lshl_add_u64 v[142:143], s[22:23], 0, v[134:135]
	s_mov_b32 m0, s34
	s_nop 0
	global_load_lds_dwordx4 v[142:143], off
	v_lshl_add_u64 v[142:143], s[22:23], 0, v[130:131]
	s_add_i32 m0, s34, 0x2000
	s_nop 0
	global_load_lds_dwordx4 v[142:143], off
	s_waitcnt vmcnt(6)
	s_barrier
	v_mfma_f32_16x16x32_f16 v[54:57], v[210:213], v[178:181], v[54:57]
	v_mfma_f32_16x16x32_f16 v[50:53], v[238:241], v[178:181], v[50:53]
	v_mfma_f32_16x16x32_f16 v[38:41], v[210:213], v[186:189], v[38:41]
	v_mfma_f32_16x16x32_f16 v[34:37], v[238:241], v[186:189], v[34:37]
	v_mfma_f32_16x16x32_f16 v[22:25], v[210:213], v[194:197], v[22:25]
	v_mfma_f32_16x16x32_f16 v[18:21], v[238:241], v[194:197], v[18:21]
	v_mfma_f32_16x16x32_f16 v[6:9], v[210:213], v[202:205], v[6:9]
	v_mfma_f32_16x16x32_f16 v[2:5], v[238:241], v[202:205], v[2:5]
	v_mfma_f32_16x16x32_f16 v[54:57], v[234:237], v[182:185], v[54:57]
	v_mfma_f32_16x16x32_f16 v[50:53], v[242:245], v[182:185], v[50:53]
	v_mfma_f32_16x16x32_f16 v[38:41], v[234:237], v[190:193], v[38:41]
	v_mfma_f32_16x16x32_f16 v[34:37], v[242:245], v[190:193], v[34:37]
	v_mfma_f32_16x16x32_f16 v[22:25], v[234:237], v[198:201], v[22:25]
	v_mfma_f32_16x16x32_f16 v[18:21], v[242:245], v[198:201], v[18:21]
	v_mfma_f32_16x16x32_f16 v[6:9], v[234:237], v[206:209], v[6:9]
	v_mfma_f32_16x16x32_f16 v[2:5], v[242:245], v[206:209], v[2:5]
	s_add_i32 s58, s58, 2
	s_add_u32 s25, s25, 0x100
	s_addc_u32 s53, s53, 0
	s_add_u32 s6, s6, 0x100
	s_addc_u32 s7, s7, 0
	s_cmp_gt_u32 s58, 29
	s_barrier
	s_cbranch_scc0 .LBB0_302
	s_cmp_lt_i32 s51, 8
	s_cselect_b64 s[34:35], -1, 0
	s_cmp_gt_i32 s51, 7
	s_cbranch_scc1 .LBB0_305
	v_mul_f32_e32 v143, 0x3d372713, v122
	v_mul_f32_e32 v143, v122, v143
	v_fma_f32 v143, v122, v143, v122
	v_mul_f32_e32 v143, 0xbfcc422a, v143
	v_mul_f32_e32 v143, 0x3fb8aa3b, v143
	v_exp_f32_e32 v143, v143
	v_mul_f32_e32 v142, 0x3d372713, v126
	v_mul_f32_e32 v142, v126, v142
	v_fma_f32 v142, v126, v142, v126
	v_add_f32_e32 v143, 1.0, v143
	v_rcp_f32_e32 v144, v143
	v_mul_f32_e32 v143, 0x3d372713, v127
	v_mul_f32_e32 v143, v127, v143
	v_fma_f32 v143, v127, v143, v127
	v_mul_f32_e32 v142, 0xbfcc422a, v142
	v_mul_f32_e32 v143, 0xbfcc422a, v143
	v_mul_f32_e32 v142, 0x3fb8aa3b, v142
	v_mul_f32_e32 v143, 0x3fb8aa3b, v143
	v_mul_f32_e32 v147, 0x3d372713, v124
	v_exp_f32_e32 v142, v142
	v_exp_f32_e32 v143, v143
	v_mul_f32_e32 v147, v124, v147
	v_fma_f32 v147, v124, v147, v124
	v_mul_f32_e32 v147, 0xbfcc422a, v147
	v_mul_f32_e32 v147, 0x3fb8aa3b, v147
	v_add_f32_e32 v142, 1.0, v142
	v_add_f32_e32 v143, 1.0, v143
	v_exp_f32_e32 v147, v147
	v_rcp_f32_e32 v142, v142
	v_rcp_f32_e32 v143, v143
	v_mul_f32_e32 v145, 0x3d372713, v123
	v_add_f32_e32 v147, 1.0, v147
	v_mul_f32_e32 v146, 0x3d372713, v128
	v_rcp_f32_e32 v152, v147
	v_mul_f32_e32 v147, 0x3d372713, v129
	v_pk_mul_f32 v[126:127], v[126:127], v[142:143]
	v_mul_f32_e32 v142, 0x3d372713, v125
	v_mul_f32_e32 v145, v123, v145
	v_mul_f32_e32 v146, v128, v146
	v_mul_f32_e32 v147, v129, v147
	v_mul_f32_e32 v142, v125, v142
	v_fma_f32 v145, v123, v145, v123
	v_fma_f32 v146, v128, v146, v128
	v_fma_f32 v147, v129, v147, v129
	v_fma_f32 v142, v125, v142, v125
	v_mul_f32_e32 v145, 0xbfcc422a, v145
	v_mul_f32_e32 v146, 0xbfcc422a, v146
	v_mul_f32_e32 v147, 0xbfcc422a, v147
	v_mul_f32_e32 v142, 0xbfcc422a, v142
	v_mul_f32_e32 v145, 0x3fb8aa3b, v145
	v_mul_f32_e32 v146, 0x3fb8aa3b, v146
	v_mul_f32_e32 v147, 0x3fb8aa3b, v147
	v_mul_f32_e32 v142, 0x3fb8aa3b, v142
	v_exp_f32_e32 v145, v145
	v_exp_f32_e32 v146, v146
	v_exp_f32_e32 v147, v147
	v_exp_f32_e32 v142, v142
	v_add_f32_e32 v145, 1.0, v145
	v_add_f32_e32 v146, 1.0, v146
	v_add_f32_e32 v147, 1.0, v147
	v_add_f32_e32 v142, 1.0, v142
	v_rcp_f32_e32 v145, v145
	v_rcp_f32_e32 v146, v146
	v_rcp_f32_e32 v147, v147
	v_rcp_f32_e32 v153, v142
	v_pk_mul_f32 v[122:123], v[122:123], v[144:145]
	v_pk_mul_f32 v[128:129], v[128:129], v[146:147]
	v_pk_mul_f32 v[124:125], v[124:125], v[152:153]

; #define PG8_STAGE(bufoff, gbase, voff) do { _Pragma("unroll") for (int _i = 0; _i < 2; ++_i) \
;         __builtin_amdgcn_global_load_lds((const unsigned*)((const char*)(gbase) + (voff)[_i]), (LAS unsigned*)(lds + (bufoff) + ldsw + _i * 8192), 16, 0, 0); } while (0)
; #define PG8_LDA(dst, b, h) do { _Pragma("unroll") for (int m = 0; m < 4; ++m) _Pragma("unroll") for (int k = 0; k < 2; ++k) dst[m][k] = *(const LAS f16x8*)(lds + PG8_SA(b, h) + aoff + m * 2048 + k * 1024); } while (0)
; #define PG8_LDB(dst, b, h) do { _Pragma("unroll") for (int n = 0; n < 2; ++n) _Pragma("unroll") for (int k = 0; k < 2; ++k) dst[n][k] = *(const LAS f16x8*)(lds + PG8_SB(b, h) + boff + n * 2048 + k * 1024); } while (0)
; #define PG8_MMA(ai, bj, At, Bt) do { __builtin_amdgcn_s_setprio(1); _Pragma("unroll") for (int m = 0; m < 4; ++m) _Pragma("unroll") for (int n = 0; n < 2; ++n) _Pragma("unroll") for (int k = 0; k < 2; ++k) \
;         acc[ai][bj][m][n] = __builtin_amdgcn_mfma_f32_16x16x32_f16(Bt[n][k], At[m][k], acc[ai][bj][m][n], 0, 0, 0); __builtin_amdgcn_s_setprio(0); } while (0)
; #define PG8_WAIT_L(n) asm volatile("s_waitcnt lgkmcnt(" #n ")" ::: "memory")
; #define PG8_BAR __builtin_amdgcn_s_barrier()
; #define PG8_SCHED __builtin_amdgcn_sched_barrier(0)
; template <class Epi>
; __device__ __forceinline__ void gemm_phase(LAS unsigned char* lds, const Gemm g0, const StaticOrder& S, const Epi& E) {
;     ...
;             PG8_LDB(B0, 0, 0); PG8_SCHED; PG8_LDA(At, 0, 0); PG8_STAGE(PG8_SA(1, 1), a1 + hstep, voffA);
;             PG8_WAIT_L(8); PG8_BAR; PG8_WAIT_L(0); PG8_MMA(0, 0, At, B0); PG8_BAR; PG8_SCHED;
;             PG8_LDB(B1, 0, 1); PG8_STAGE(PG8_SB(0, 0), b2, voffB);
;             PG8_BAR; PG8_WAIT_L(0); PG8_MMA(0, 1, At, B1); PG8_BAR;
;             PG8_LDA(At, 0, 1); PG8_STAGE(PG8_SA(0, 0), a2, voffA);
;             PG8_BAR; PG8_WAIT_L(0); PG8_MMA(1, 0, At, B0); PG8_BAR; PG8_SCHED;
.LBB0_512:
	s_add_u32 s23, s12, 0xfff80080
	s_addc_u32 s48, s13, -1
	s_add_i32 s90, 0, 0x10000
	v_add_u32_e32 v142, s90, v205
	ds_read_b128 v[122:125], v142
	ds_read_b128 v[126:129], v142 offset:1024
	ds_read_b128 v[138:141], v142 offset:2048
	ds_read_b128 v[142:145], v142 offset:3072
	s_cmp_eq_u32 s22, 28
	s_cselect_b32 s51, s15, s48
	s_cselect_b32 s50, s24, s23
	s_cselect_b32 s49, s25, vcc_hi
	s_cselect_b32 s48, s53, vcc_lo
	v_lshl_add_u64 v[162:163], s[12:13], 0, v[186:187]
	s_add_i32 m0, s71, 0xc000
	ds_read_b128 v[146:149], v210
	ds_read_b128 v[150:153], v210 offset:1024
	ds_read_b128 v[154:157], v210 offset:2048
	ds_read_b128 v[158:161], v210 offset:3072
	ds_read_b128 v[188:191], v210 offset:4096
	ds_read_b128 v[192:195], v210 offset:5120
	ds_read_b128 v[196:199], v210 offset:6144
	ds_read_b128 v[200:203], v210 offset:7168
	global_load_lds_dwordx4 v[162:163], off
	v_lshl_add_u64 v[162:163], s[12:13], 0, v[184:185]
	s_add_i32 m0, s71, 0xe000
	s_nop 0
	global_load_lds_dwordx4 v[162:163], off
	s_waitcnt lgkmcnt(8)
	s_barrier
	s_waitcnt lgkmcnt(0)
	s_waitcnt lgkmcnt(0)
	v_mfma_f32_16x16x32_f16 v[134:137], v[122:125], v[146:149], v[134:137]
	v_mfma_f32_16x16x32_f16 v[130:133], v[138:141], v[146:149], v[130:133]
	v_mfma_f32_16x16x32_f16 v[110:113], v[122:125], v[154:157], v[110:113]
	v_mfma_f32_16x16x32_f16 v[106:109], v[138:141], v[154:157], v[106:109]
	v_mfma_f32_16x16x32_f16 v[94:97], v[122:125], v[188:191], v[94:97]
	v_mfma_f32_16x16x32_f16 v[90:93], v[138:141], v[188:191], v[90:93]
	v_mfma_f32_16x16x32_f16 v[78:81], v[122:125], v[196:199], v[78:81]
	v_mfma_f32_16x16x32_f16 v[74:77], v[138:141], v[196:199], v[74:77]
	v_mfma_f32_16x16x32_f16 v[134:137], v[126:129], v[150:153], v[134:137]
	v_mfma_f32_16x16x32_f16 v[130:133], v[142:145], v[150:153], v[130:133]
	v_mfma_f32_16x16x32_f16 v[110:113], v[126:129], v[158:161], v[110:113]
	v_mfma_f32_16x16x32_f16 v[106:109], v[142:145], v[158:161], v[106:109]
	v_mfma_f32_16x16x32_f16 v[94:97], v[126:129], v[192:195], v[94:97]
	v_mfma_f32_16x16x32_f16 v[90:93], v[142:145], v[192:195], v[90:93]
	v_mfma_f32_16x16x32_f16 v[78:81], v[126:129], v[200:203], v[78:81]
	v_mfma_f32_16x16x32_f16 v[74:77], v[142:145], v[200:203], v[74:77]
	s_barrier
	s_add_i32 s23, 0, 0x14000
	v_add_u32_e32 v162, s23, v205
	s_add_i32 s90, s90, s75
	ds_read_b128 v[212:215], v162
	ds_read_b128 v[234:237], v162 offset:1024
	ds_read_b128 v[238:241], v162 offset:2048
	ds_read_b128 v[242:245], v162 offset:3072
	v_lshl_add_u64 v[162:163], s[48:49], 0, v[178:179]
	s_mov_b32 m0, s90
	v_lshl_add_u64 v[164:165], s[48:49], 0, v[174:175]
	global_load_lds_dwordx4 v[162:163], off
	s_add_i32 m0, s90, 0x2000
	s_nop 0
	global_load_lds_dwordx4 v[164:165], off
	s_barrier
	s_waitcnt lgkmcnt(0)
	s_waitcnt lgkmcnt(0)
	v_mfma_f32_16x16x32_f16 v[118:121], v[212:215], v[146:149], v[118:121]
	v_mfma_f32_16x16x32_f16 v[114:117], v[238:241], v[146:149], v[114:117]
	v_mfma_f32_16x16x32_f16 v[102:105], v[212:215], v[154:157], v[102:105]
	v_mfma_f32_16x16x32_f16 v[98:101], v[238:241], v[154:157], v[98:101]
	v_mfma_f32_16x16x32_f16 v[86:89], v[212:215], v[188:191], v[86:89]
	v_mfma_f32_16x16x32_f16 v[82:85], v[238:241], v[188:191], v[82:85]
	v_mfma_f32_16x16x32_f16 v[70:73], v[212:215], v[196:199], v[70:73]
	v_mfma_f32_16x16x32_f16 v[66:69], v[238:241], v[196:199], v[66:69]
	v_mfma_f32_16x16x32_f16 v[118:121], v[234:237], v[150:153], v[118:121]
	v_mfma_f32_16x16x32_f16 v[114:117], v[242:245], v[150:153], v[114:117]
	v_mfma_f32_16x16x32_f16 v[102:105], v[234:237], v[158:161], v[102:105]
	v_mfma_f32_16x16x32_f16 v[98:101], v[242:245], v[158:161], v[98:101]
	v_mfma_f32_16x16x32_f16 v[86:89], v[234:237], v[192:195], v[86:89]
	v_mfma_f32_16x16x32_f16 v[82:85], v[242:245], v[192:195], v[82:85]
	v_mfma_f32_16x16x32_f16 v[70:73], v[234:237], v[200:203], v[70:73]
	v_mfma_f32_16x16x32_f16 v[66:69], v[242:245], v[200:203], v[66:69]
	s_mov_b32 m0, s71
	v_lshl_add_u64 v[170:171], s[50:51], 0, v[180:181]
	s_barrier
	ds_read_b128 v[146:149], v210 offset:16384
	ds_read_b128 v[150:153], v210 offset:17408
	ds_read_b128 v[154:157], v210 offset:18432
	ds_read_b128 v[158:161], v210 offset:19456
	ds_read_b128 v[188:191], v210 offset:20480
	ds_read_b128 v[192:195], v210 offset:21504
	ds_read_b128 v[196:199], v210 offset:22528
	ds_read_b128 v[200:203], v210 offset:23552
	global_load_lds_dwordx4 v[170:171], off
	v_lshl_add_u64 v[172:173], s[50:51], 0, v[176:177]
	s_mov_b32 m0, s61
	s_nop 0
	global_load_lds_dwordx4 v[172:173], off
	s_barrier
	s_waitcnt lgkmcnt(0)
	s_waitcnt lgkmcnt(0)
	v_mfma_f32_16x16x32_f16 v[62:65], v[122:125], v[146:149], v[62:65]
	v_mfma_f32_16x16x32_f16 v[58:61], v[138:141], v[146:149], v[58:61]
	v_mfma_f32_16x16x32_f16 v[46:49], v[122:125], v[154:157], v[46:49]
	v_mfma_f32_16x16x32_f16 v[42:45], v[138:141], v[154:157], v[42:45]
	v_mfma_f32_16x16x32_f16 v[30:33], v[122:125], v[188:191], v[30:33]
	v_mfma_f32_16x16x32_f16 v[26:29], v[138:141], v[188:191], v[26:29]
	v_mfma_f32_16x16x32_f16 v[14:17], v[122:125], v[196:199], v[14:17]
	v_mfma_f32_16x16x32_f16 v[10:13], v[138:141], v[196:199], v[10:13]
	v_mfma_f32_16x16x32_f16 v[62:65], v[126:129], v[150:153], v[62:65]
	v_mfma_f32_16x16x32_f16 v[58:61], v[142:145], v[150:153], v[58:61]
	v_mfma_f32_16x16x32_f16 v[46:49], v[126:129], v[158:161], v[46:49]
	v_mfma_f32_16x16x32_f16 v[42:45], v[142:145], v[158:161], v[42:45]
	v_mfma_f32_16x16x32_f16 v[30:33], v[126:129], v[192:195], v[30:33]
	v_mfma_f32_16x16x32_f16 v[26:29], v[142:145], v[192:195], v[26:29]
	v_mfma_f32_16x16x32_f16 v[14:17], v[126:129], v[200:203], v[14:17]
	v_mfma_f32_16x16x32_f16 v[10:13], v[142:145], v[200:203], v[10:13]
	s_barrier
; #define PG8_STAGE(bufoff, gbase, voff) do { _Pragma("unroll") for (int _i = 0; _i < 2; ++_i) \
;         __builtin_amdgcn_global_load_lds((const unsigned*)((const char*)(gbase) + (voff)[_i]), (LAS unsigned*)(lds + (bufoff) + ldsw + _i * 8192), 16, 0, 0); } while (0)
; #define PG8_LDA(dst, b, h) do { _Pragma("unroll") for (int m = 0; m < 4; ++m) _Pragma("unroll") for (int k = 0; k < 2; ++k) dst[m][k] = *(const LAS f16x8*)(lds + PG8_SA(b, h) + aoff + m * 2048 + k * 1024); } while (0)
; #define PG8_LDB(dst, b, h) do { _Pragma("unroll") for (int n = 0; n < 2; ++n) _Pragma("unroll") for (int k = 0; k < 2; ++k) dst[n][k] = *(const LAS f16x8*)(lds + PG8_SB(b, h) + boff + n * 2048 + k * 1024); } while (0)
; #define PG8_MMA(ai, bj, At, Bt) do { __builtin_amdgcn_s_setprio(1); _Pragma("unroll") for (int m = 0; m < 4; ++m) _Pragma("unroll") for (int n = 0; n < 2; ++n) _Pragma("unroll") for (int k = 0; k < 2; ++k) \
;         acc[ai][bj][m][n] = __builtin_amdgcn_mfma_f32_16x16x32_f16(Bt[n][k], At[m][k], acc[ai][bj][m][n], 0, 0, 0); __builtin_amdgcn_s_setprio(0); } while (0)
; #define PG8_WAIT_V(n) asm volatile("s_waitcnt vmcnt(" #n ")" ::: "memory")
; #define PG8_WAIT_L(n) asm volatile("s_waitcnt lgkmcnt(" #n ")" ::: "memory")
; #define PG8_BAR __builtin_amdgcn_s_barrier()
; #define PG8_SCHED __builtin_amdgcn_sched_barrier(0)
; template <class Epi>
; __device__ __forceinline__ void gemm_phase(LAS unsigned char* lds, const Gemm g0, const StaticOrder& S, const Epi& E) {
;     ...
;             PG8_STAGE(PG8_SB(0, 1), b2 + hstep, voffB);
;             PG8_WAIT_V(6); PG8_BAR; PG8_MMA(1, 1, At, B1); PG8_BAR;
;             PG8_LDB(B0, 1, 0); PG8_SCHED; PG8_LDA(At, 1, 0); PG8_STAGE(PG8_SA(0, 1), a2 + hstep, voffA);
;             PG8_WAIT_L(8); PG8_BAR; PG8_WAIT_L(0); PG8_MMA(0, 0, At, B0); PG8_BAR; PG8_SCHED;
	s_add_u32 s90, s48, 0x80000
	s_addc_u32 s91, s49, 0
	s_add_i32 s23, s23, s75
	v_lshl_add_u64 v[122:123], s[90:91], 0, v[178:179]
	s_mov_b32 m0, s23
	s_nop 0
	global_load_lds_dwordx4 v[122:123], off
	v_lshl_add_u64 v[122:123], s[90:91], 0, v[174:175]
	s_add_i32 m0, s23, 0x2000
	s_nop 0
	global_load_lds_dwordx4 v[122:123], off
	s_waitcnt vmcnt(6)
	s_barrier
	v_mfma_f32_16x16x32_f16 v[54:57], v[212:215], v[146:149], v[54:57]
	v_mfma_f32_16x16x32_f16 v[50:53], v[238:241], v[146:149], v[50:53]
	v_mfma_f32_16x16x32_f16 v[38:41], v[212:215], v[154:157], v[38:41]
	v_mfma_f32_16x16x32_f16 v[34:37], v[238:241], v[154:157], v[34:37]
	v_mfma_f32_16x16x32_f16 v[22:25], v[212:215], v[188:191], v[22:25]
	v_mfma_f32_16x16x32_f16 v[18:21], v[238:241], v[188:191], v[18:21]
	v_mfma_f32_16x16x32_f16 v[6:9], v[212:215], v[196:199], v[6:9]
	v_mfma_f32_16x16x32_f16 v[2:5], v[238:241], v[196:199], v[2:5]
	v_mfma_f32_16x16x32_f16 v[54:57], v[234:237], v[150:153], v[54:57]
	v_mfma_f32_16x16x32_f16 v[50:53], v[242:245], v[150:153], v[50:53]
	v_mfma_f32_16x16x32_f16 v[38:41], v[234:237], v[158:161], v[38:41]
	v_mfma_f32_16x16x32_f16 v[34:37], v[242:245], v[158:161], v[34:37]
	v_mfma_f32_16x16x32_f16 v[22:25], v[234:237], v[192:195], v[22:25]
	v_mfma_f32_16x16x32_f16 v[18:21], v[242:245], v[192:195], v[18:21]
	v_mfma_f32_16x16x32_f16 v[6:9], v[234:237], v[200:203], v[6:9]
	v_mfma_f32_16x16x32_f16 v[2:5], v[242:245], v[200:203], v[2:5]
	s_add_i32 s23, 0, 0x18000
	v_add_u32_e32 v142, s23, v205
	s_barrier
	ds_read_b128 v[122:125], v142
	ds_read_b128 v[126:129], v142 offset:1024
	ds_read_b128 v[138:141], v142 offset:2048
	ds_read_b128 v[142:145], v142 offset:3072
	s_add_u32 s50, s50, 0x80000
	s_addc_u32 s51, s51, 0
	s_mov_b32 m0, s74
	v_lshl_add_u64 v[212:213], s[50:51], 0, v[180:181]
	ds_read_b128 v[146:149], v210 offset:32768
	ds_read_b128 v[150:153], v210 offset:33792
	ds_read_b128 v[154:157], v210 offset:34816
	ds_read_b128 v[158:161], v210 offset:35840
	ds_read_b128 v[188:191], v210 offset:36864
	ds_read_b128 v[192:195], v210 offset:37888
	ds_read_b128 v[196:199], v210 offset:38912
	ds_read_b128 v[200:203], v210 offset:39936
	global_load_lds_dwordx4 v[212:213], off
	v_lshl_add_u64 v[212:213], s[50:51], 0, v[176:177]
	s_mov_b32 m0, s18
	s_nop 0
	global_load_lds_dwordx4 v[212:213], off
	s_waitcnt lgkmcnt(8)
	s_barrier
	s_waitcnt lgkmcnt(0)
	s_waitcnt lgkmcnt(0)
	v_mfma_f32_16x16x32_f16 v[134:137], v[122:125], v[146:149], v[134:137]
	v_mfma_f32_16x16x32_f16 v[130:133], v[138:141], v[146:149], v[130:133]
	v_mfma_f32_16x16x32_f16 v[110:113], v[122:125], v[154:157], v[110:113]
	v_mfma_f32_16x16x32_f16 v[106:109], v[138:141], v[154:157], v[106:109]
	v_mfma_f32_16x16x32_f16 v[94:97], v[122:125], v[188:191], v[94:97]
	v_mfma_f32_16x16x32_f16 v[90:93], v[138:141], v[188:191], v[90:93]
	v_mfma_f32_16x16x32_f16 v[78:81], v[122:125], v[196:199], v[78:81]
	v_mfma_f32_16x16x32_f16 v[74:77], v[138:141], v[196:199], v[74:77]
	v_mfma_f32_16x16x32_f16 v[134:137], v[126:129], v[150:153], v[134:137]
	v_mfma_f32_16x16x32_f16 v[130:133], v[142:145], v[150:153], v[130:133]
	v_mfma_f32_16x16x32_f16 v[110:113], v[126:129], v[158:161], v[110:113]
	v_mfma_f32_16x16x32_f16 v[106:109], v[142:145], v[158:161], v[106:109]
	v_mfma_f32_16x16x32_f16 v[94:97], v[126:129], v[192:195], v[94:97]
	v_mfma_f32_16x16x32_f16 v[90:93], v[142:145], v[192:195], v[90:93]
	v_mfma_f32_16x16x32_f16 v[78:81], v[126:129], v[200:203], v[78:81]
	v_mfma_f32_16x16x32_f16 v[74:77], v[142:145], v[200:203], v[74:77]
	s_barrier
	s_add_i32 s50, 0, 0x1c000
	s_add_i32 s23, s23, s75
	v_add_u32_e32 v211, s50, v205
	v_lshl_add_u64 v[162:163], v[162:163], 0, s[64:65]
	s_mov_b32 m0, s23
	ds_read_b128 v[212:215], v211
	ds_read_b128 v[234:237], v211 offset:1024
	ds_read_b128 v[238:241], v211 offset:2048
	ds_read_b128 v[242:245], v211 offset:3072
	global_load_lds_dwordx4 v[162:163], off
	v_lshl_add_u64 v[162:163], v[164:165], 0, s[64:65]
	s_add_i32 m0, s23, 0x2000
	s_nop 0
	global_load_lds_dwordx4 v[162:163], off
	s_barrier
; #define LAS __attribute__((address_space(3)))
; #define GAS __attribute__((address_space(1)))
; #define PG8_STAGE(bufoff, gbase, voff) do { _Pragma("unroll") for (int _i = 0; _i < 2; ++_i) \
;         __builtin_amdgcn_global_load_lds((const unsigned*)((const char*)(gbase) + (voff)[_i]), (LAS unsigned*)(lds + (bufoff) + ldsw + _i * 8192), 16, 0, 0); } while (0)
; #define PG8_LDA(dst, b, h) do { _Pragma("unroll") for (int m = 0; m < 4; ++m) _Pragma("unroll") for (int k = 0; k < 2; ++k) dst[m][k] = *(const LAS f16x8*)(lds + PG8_SA(b, h) + aoff + m * 2048 + k * 1024); } while (0)
; #define PG8_LDB(dst, b, h) do { _Pragma("unroll") for (int n = 0; n < 2; ++n) _Pragma("unroll") for (int k = 0; k < 2; ++k) dst[n][k] = *(const LAS f16x8*)(lds + PG8_SB(b, h) + boff + n * 2048 + k * 1024); } while (0)
; #define PG8_WAIT_V(n) asm volatile("s_waitcnt vmcnt(" #n ")" ::: "memory")
; #define PG8_WAIT_L(n) asm volatile("s_waitcnt lgkmcnt(" #n ")" ::: "memory")
; #define PG8_BAR __builtin_amdgcn_s_barrier()
; #define PG8_SCHED __builtin_amdgcn_sched_barrier(0)
;     __device__ __forceinline__ void operator()(f32x4 (&acc)[2][2][4][2], const Unit& u, int wr, int wc, int fr, int fq) const {
;         const int row0 = u.pm * BM + wr * 64 + fr, colb = u.pn * BM + wc * 32 + 8 * fq;
;         const bool hasln = pstats != nullptr, haszh = zh != nullptr;
;         LAS float* slot = vl + (wr * 4 + wc) * 256;
;         f32x4 rn[2][2]; float ssm[8], ssq[8]; f32x2 stn = {0.f, 0.f};
;         { const int lane = fr + 16 * fq, cL = u.pn * BM + wc * 32 + (lane < 32 ? lane : 96 + lane);
;           float vg = 0.f, vb = 0.f, vt = 0.f;
;           if (hasln) { vg = *(const GAS float*)(pg + cL); vb = *(const GAS float*)(pb + cL); }
; template <class Epi>
; __device__ __forceinline__ void gemm_phase(LAS unsigned char* lds, const Gemm g0, const StaticOrder& S, const Epi& E) {
;     ...
;             PG8_LDB(B1, 1, 1); PG8_STAGE(PG8_SB(1, 0), b3, voffB);
;             PG8_BAR; PG8_WAIT_L(0); PG8_MMA(0, 1, At, B1); PG8_BAR;
;             PG8_LDA(At, 1, 1); PG8_STAGE(PG8_SA(1, 0), a3, voffA);
;             PG8_BAR; PG8_WAIT_L(0); PG8_MMA(1, 0, At, B0); PG8_BAR; PG8_SCHED;
;             PG8_STAGE(PG8_SB(1, 1), b3 + hstep, voffB);
;             PG8_WAIT_V(6); PG8_BAR; PG8_MMA(1, 1, At, B1); PG8_BAR;
	s_waitcnt lgkmcnt(0)
	s_waitcnt lgkmcnt(0)
	v_mfma_f32_16x16x32_f16 v[118:121], v[212:215], v[146:149], v[118:121]
	v_mfma_f32_16x16x32_f16 v[114:117], v[238:241], v[146:149], v[114:117]
	v_mfma_f32_16x16x32_f16 v[102:105], v[212:215], v[154:157], v[102:105]
	v_mfma_f32_16x16x32_f16 v[98:101], v[238:241], v[154:157], v[98:101]
	v_mfma_f32_16x16x32_f16 v[86:89], v[212:215], v[188:191], v[86:89]
	v_mfma_f32_16x16x32_f16 v[82:85], v[238:241], v[188:191], v[82:85]
	v_mfma_f32_16x16x32_f16 v[70:73], v[212:215], v[196:199], v[70:73]
	v_mfma_f32_16x16x32_f16 v[66:69], v[238:241], v[196:199], v[66:69]
	v_mfma_f32_16x16x32_f16 v[118:121], v[234:237], v[150:153], v[118:121]
	v_mfma_f32_16x16x32_f16 v[114:117], v[242:245], v[150:153], v[114:117]
	v_mfma_f32_16x16x32_f16 v[102:105], v[234:237], v[158:161], v[102:105]
	v_mfma_f32_16x16x32_f16 v[98:101], v[242:245], v[158:161], v[98:101]
	v_mfma_f32_16x16x32_f16 v[86:89], v[234:237], v[192:195], v[86:89]
	v_mfma_f32_16x16x32_f16 v[82:85], v[242:245], v[192:195], v[82:85]
	v_mfma_f32_16x16x32_f16 v[70:73], v[234:237], v[200:203], v[70:73]
	v_mfma_f32_16x16x32_f16 v[66:69], v[242:245], v[200:203], v[66:69]
	s_mov_b32 m0, s28
	v_lshl_add_u64 v[162:163], v[170:171], 0, s[64:65]
	s_barrier
	ds_read_b128 v[146:149], v210 offset:49152
	ds_read_b128 v[150:153], v210 offset:50176
	ds_read_b128 v[154:157], v210 offset:51200
	ds_read_b128 v[158:161], v210 offset:52224
	ds_read_b128 v[188:191], v210 offset:53248
	ds_read_b128 v[192:195], v210 offset:54272
	ds_read_b128 v[196:199], v210 offset:55296
	ds_read_b128 v[200:203], v210 offset:56320
	global_load_lds_dwordx4 v[162:163], off
	v_lshl_add_u64 v[162:163], v[172:173], 0, s[64:65]
	s_mov_b32 m0, s29
	s_nop 0
	global_load_lds_dwordx4 v[162:163], off
	s_barrier
	s_waitcnt lgkmcnt(0)
	s_waitcnt lgkmcnt(0)
	v_mfma_f32_16x16x32_f16 v[62:65], v[122:125], v[146:149], v[62:65]
	v_mfma_f32_16x16x32_f16 v[58:61], v[138:141], v[146:149], v[58:61]
	v_mfma_f32_16x16x32_f16 v[46:49], v[122:125], v[154:157], v[46:49]
	v_mfma_f32_16x16x32_f16 v[42:45], v[138:141], v[154:157], v[42:45]
	v_mfma_f32_16x16x32_f16 v[30:33], v[122:125], v[188:191], v[30:33]
	v_mfma_f32_16x16x32_f16 v[26:29], v[138:141], v[188:191], v[26:29]
	v_mfma_f32_16x16x32_f16 v[14:17], v[122:125], v[196:199], v[14:17]
	v_mfma_f32_16x16x32_f16 v[10:13], v[138:141], v[196:199], v[10:13]
	v_mfma_f32_16x16x32_f16 v[62:65], v[126:129], v[150:153], v[62:65]
	v_mfma_f32_16x16x32_f16 v[58:61], v[142:145], v[150:153], v[58:61]
	v_mfma_f32_16x16x32_f16 v[46:49], v[126:129], v[158:161], v[46:49]
	v_mfma_f32_16x16x32_f16 v[42:45], v[142:145], v[158:161], v[42:45]
	v_mfma_f32_16x16x32_f16 v[30:33], v[126:129], v[192:195], v[30:33]
	v_mfma_f32_16x16x32_f16 v[26:29], v[142:145], v[192:195], v[26:29]
	v_mfma_f32_16x16x32_f16 v[14:17], v[126:129], v[200:203], v[14:17]
	v_mfma_f32_16x16x32_f16 v[10:13], v[142:145], v[200:203], v[10:13]
	s_barrier
	s_add_u32 s48, s48, 0x80080
	s_addc_u32 s49, s49, 0
	s_add_i32 s23, s50, s75
	v_lshl_add_u64 v[122:123], s[48:49], 0, v[178:179]
	s_mov_b32 m0, s23
	s_nop 0
	global_load_lds_dwordx4 v[122:123], off
	v_lshl_add_u64 v[122:123], s[48:49], 0, v[174:175]
	s_add_i32 m0, s23, 0x2000
	s_nop 0
	global_load_lds_dwordx4 v[122:123], off
	s_waitcnt vmcnt(6)
	s_barrier
	v_mfma_f32_16x16x32_f16 v[54:57], v[212:215], v[146:149], v[54:57]
	v_mfma_f32_16x16x32_f16 v[50:53], v[238:241], v[146:149], v[50:53]
	v_mfma_f32_16x16x32_f16 v[38:41], v[212:215], v[154:157], v[38:41]
	v_mfma_f32_16x16x32_f16 v[34:37], v[238:241], v[154:157], v[34:37]
	v_mfma_f32_16x16x32_f16 v[22:25], v[212:215], v[188:191], v[22:25]
	v_mfma_f32_16x16x32_f16 v[18:21], v[238:241], v[188:191], v[18:21]
	v_mfma_f32_16x16x32_f16 v[6:9], v[212:215], v[196:199], v[6:9]
	v_mfma_f32_16x16x32_f16 v[2:5], v[238:241], v[196:199], v[2:5]
	v_mfma_f32_16x16x32_f16 v[54:57], v[234:237], v[150:153], v[54:57]
	v_mfma_f32_16x16x32_f16 v[50:53], v[242:245], v[150:153], v[50:53]
	v_mfma_f32_16x16x32_f16 v[38:41], v[234:237], v[158:161], v[38:41]
	v_mfma_f32_16x16x32_f16 v[34:37], v[242:245], v[158:161], v[34:37]
	v_mfma_f32_16x16x32_f16 v[22:25], v[234:237], v[192:195], v[22:25]
	v_mfma_f32_16x16x32_f16 v[18:21], v[242:245], v[192:195], v[18:21]
	v_mfma_f32_16x16x32_f16 v[6:9], v[234:237], v[200:203], v[6:9]
	v_mfma_f32_16x16x32_f16 v[2:5], v[242:245], v[200:203], v[2:5]
	s_add_i32 s22, s22, 2
	s_add_u32 vcc_lo, vcc_lo, 0x100
	s_addc_u32 vcc_hi, vcc_hi, 0
	s_add_u32 s12, s12, 0x100
	s_addc_u32 s13, s13, 0
	s_cmp_gt_u32 s22, 29
	s_barrier
	s_cbranch_scc0 .LBB0_512
	s_lshl_b32 s12, s83, 8
	s_or_b32 s15, s12, s31
	v_add_u32_e32 v122, s15, v206
	v_cndmask_b32_e64 v124, 0, 1, s[44:45]
	v_ashrrev_i32_e32 v123, 31, v122
	v_mov_b32_e32 v196, 0
	v_cmp_ne_u32_e64 s[12:13], 1, v124
	s_andn2_b64 vcc, exec, s[44:45]
	v_mov_b32_e32 v124, 0
	v_mov_b32_e32 v125, 0
	s_cbranch_vccnz .LBB0_515
	v_lshlrev_b64 v[124:125], 2, v[122:123]
	v_lshl_add_u64 v[126:127], s[80:81], 0, v[124:125]
	v_lshl_add_u64 v[124:125], s[58:59], 0, v[124:125]
	global_load_dword v125, v[124:125], off
	s_nop 0
	global_load_dword v124, v[126:127], off

; #define PG8_STAGE(bufoff, gbase, voff) do { _Pragma("unroll") for (int _i = 0; _i < 2; ++_i) \
;         __builtin_amdgcn_global_load_lds((const unsigned*)((const char*)(gbase) + (voff)[_i]), (LAS unsigned*)(lds + (bufoff) + ldsw + _i * 8192), 16, 0, 0); } while (0)
; #define PG8_LDA(dst, b, h) do { _Pragma("unroll") for (int m = 0; m < 4; ++m) _Pragma("unroll") for (int k = 0; k < 2; ++k) dst[m][k] = *(const LAS f16x8*)(lds + PG8_SA(b, h) + aoff + m * 2048 + k * 1024); } while (0)
; #define PG8_LDB(dst, b, h) do { _Pragma("unroll") for (int n = 0; n < 2; ++n) _Pragma("unroll") for (int k = 0; k < 2; ++k) dst[n][k] = *(const LAS f16x8*)(lds + PG8_SB(b, h) + boff + n * 2048 + k * 1024); } while (0)
; #define PG8_MMA(ai, bj, At, Bt) do { __builtin_amdgcn_s_setprio(1); _Pragma("unroll") for (int m = 0; m < 4; ++m) _Pragma("unroll") for (int n = 0; n < 2; ++n) _Pragma("unroll") for (int k = 0; k < 2; ++k) \
;         acc[ai][bj][m][n] = __builtin_amdgcn_mfma_f32_16x16x32_f16(Bt[n][k], At[m][k], acc[ai][bj][m][n], 0, 0, 0); __builtin_amdgcn_s_setprio(0); } while (0)
; #define PG8_WAIT_L(n) asm volatile("s_waitcnt lgkmcnt(" #n ")" ::: "memory")
; #define PG8_BAR __builtin_amdgcn_s_barrier()
; #define PG8_SCHED __builtin_amdgcn_sched_barrier(0)
; template <class Epi>
; __device__ __forceinline__ void gemm_phase(LAS unsigned char* lds, const Gemm g0, const StaticOrder& S, const Epi& E) {
;     ...
;             PG8_LDB(B0, 0, 0); PG8_SCHED; PG8_LDA(At, 0, 0); PG8_STAGE(PG8_SA(1, 1), a1 + hstep, voffA);
;             PG8_WAIT_L(8); PG8_BAR; PG8_WAIT_L(0); PG8_MMA(0, 0, At, B0); PG8_BAR; PG8_SCHED;
;             PG8_LDB(B1, 0, 1); PG8_STAGE(PG8_SB(0, 0), b2, voffB);
;             PG8_BAR; PG8_WAIT_L(0); PG8_MMA(0, 1, At, B1); PG8_BAR;
;             PG8_LDA(At, 0, 1); PG8_STAGE(PG8_SA(0, 0), a2, voffA);
;             PG8_BAR; PG8_WAIT_L(0); PG8_MMA(1, 0, At, B0); PG8_BAR; PG8_SCHED;
.LBB0_620:
	s_add_u32 s58, s50, 0xfff80080
	s_addc_u32 s59, s51, -1
	s_and_b64 s[22:23], s[52:53], exec
	s_cselect_b32 s59, s37, s59
	s_cselect_b32 s58, s74, s58
	s_add_i32 s82, 0, 0x10000
	v_add_u32_e32 v68, s82, v189
	ds_read_b128 v[60:63], v68
	ds_read_b128 v[64:67], v68 offset:1024
	ds_read_b128 v[78:81], v68 offset:2048
	ds_read_b128 v[82:85], v68 offset:3072
	s_and_b64 s[22:23], s[52:53], exec
	s_cselect_b32 s53, s35, s25
	s_cselect_b32 s52, s75, s24
	v_lshl_add_u64 v[68:69], s[50:51], 0, v[184:185]
	s_add_i32 m0, s18, 0xc000
	ds_read_b128 v[86:89], v213
	ds_read_b128 v[90:93], v213 offset:1024
	ds_read_b128 v[194:197], v213 offset:2048
	ds_read_b128 v[234:237], v213 offset:3072
	ds_read_b128 v[238:241], v213 offset:4096
	ds_read_b128 v[242:245], v213 offset:5120
	ds_read_b128 v[246:249], v213 offset:6144
	ds_read_b128 v[226:229], v213 offset:7168
	global_load_lds_dwordx4 v[68:69], off
	v_lshl_add_u64 v[68:69], s[50:51], 0, v[182:183]
	s_add_i32 m0, s18, 0xe000
	s_nop 0
	global_load_lds_dwordx4 v[68:69], off
	s_waitcnt lgkmcnt(8)
	s_barrier
	s_waitcnt lgkmcnt(0)
	s_waitcnt lgkmcnt(0)
	v_mfma_f32_16x16x32_f16 v[158:161], v[60:63], v[86:89], v[158:161]
	v_mfma_f32_16x16x32_f16 v[150:153], v[78:81], v[86:89], v[150:153]
	v_mfma_f32_16x16x32_f16 v[142:145], v[60:63], v[194:197], v[142:145]
	v_mfma_f32_16x16x32_f16 v[134:137], v[78:81], v[194:197], v[134:137]
	v_mfma_f32_16x16x32_f16 v[126:129], v[60:63], v[238:241], v[126:129]
	v_mfma_f32_16x16x32_f16 v[118:121], v[78:81], v[238:241], v[118:121]
	v_mfma_f32_16x16x32_f16 v[110:113], v[60:63], v[246:249], v[110:113]
	v_mfma_f32_16x16x32_f16 v[102:105], v[78:81], v[246:249], v[102:105]
	v_mfma_f32_16x16x32_f16 v[158:161], v[64:67], v[90:93], v[158:161]
	v_mfma_f32_16x16x32_f16 v[150:153], v[82:85], v[90:93], v[150:153]
	v_mfma_f32_16x16x32_f16 v[142:145], v[64:67], v[234:237], v[142:145]
	v_mfma_f32_16x16x32_f16 v[134:137], v[82:85], v[234:237], v[134:137]
	v_mfma_f32_16x16x32_f16 v[126:129], v[64:67], v[242:245], v[126:129]
	v_mfma_f32_16x16x32_f16 v[118:121], v[82:85], v[242:245], v[118:121]
	v_mfma_f32_16x16x32_f16 v[110:113], v[64:67], v[226:229], v[110:113]
	v_mfma_f32_16x16x32_f16 v[102:105], v[82:85], v[226:229], v[102:105]
	s_barrier
	s_add_i32 s83, 0, 0x14000
	s_add_i32 s22, s82, s5
	v_add_u32_e32 v68, s83, v189
	v_lshl_add_u64 v[186:187], s[52:53], 0, v[178:179]
	s_mov_b32 m0, s22
	ds_read_b128 v[162:165], v68
	ds_read_b128 v[222:225], v68 offset:1024
	ds_read_b128 v[214:217], v68 offset:2048
	ds_read_b128 v[170:173], v68 offset:3072
	global_load_lds_dwordx4 v[186:187], off
	v_lshl_add_u64 v[190:191], s[52:53], 0, v[174:175]
	s_add_i32 m0, s22, 0x2000
	s_nop 0
	global_load_lds_dwordx4 v[190:191], off
	s_barrier
	s_waitcnt lgkmcnt(0)
	s_waitcnt lgkmcnt(0)
	v_mfma_f32_16x16x32_f16 v[154:157], v[162:165], v[86:89], v[154:157]
	v_mfma_f32_16x16x32_f16 v[86:89], v[214:217], v[86:89], v[146:149]
	v_mfma_f32_16x16x32_f16 v[130:133], v[214:217], v[194:197], v[130:133]
	v_mfma_f32_16x16x32_f16 v[122:125], v[162:165], v[238:241], v[122:125]
	v_mfma_f32_16x16x32_f16 v[114:117], v[214:217], v[238:241], v[114:117]
	v_mfma_f32_16x16x32_f16 v[106:109], v[162:165], v[246:249], v[106:109]
	v_mfma_f32_16x16x32_f16 v[98:101], v[214:217], v[246:249], v[98:101]
	v_mfma_f32_16x16x32_f16 v[154:157], v[222:225], v[90:93], v[154:157]
	v_mfma_f32_16x16x32_f16 v[86:89], v[170:173], v[90:93], v[86:89]
	v_mfma_f32_16x16x32_f16 v[90:93], v[162:165], v[194:197], v[138:141]
	v_mfma_f32_16x16x32_f16 v[130:133], v[170:173], v[234:237], v[130:133]
	v_mfma_f32_16x16x32_f16 v[122:125], v[222:225], v[242:245], v[122:125]
	v_mfma_f32_16x16x32_f16 v[114:117], v[170:173], v[242:245], v[114:117]
	v_mfma_f32_16x16x32_f16 v[106:109], v[222:225], v[226:229], v[106:109]
	v_mfma_f32_16x16x32_f16 v[98:101], v[170:173], v[226:229], v[98:101]
	v_mfma_f32_16x16x32_f16 v[90:93], v[222:225], v[234:237], v[90:93]
	s_mov_b32 m0, s18
	v_lshl_add_u64 v[198:199], s[58:59], 0, v[180:181]
	s_barrier
	ds_read_b128 v[138:141], v213 offset:16384
	ds_read_b128 v[146:149], v213 offset:17408
	ds_read_b128 v[194:197], v213 offset:18432
	ds_read_b128 v[226:229], v213 offset:19456
	ds_read_b128 v[234:237], v213 offset:20480
	ds_read_b128 v[238:241], v213 offset:21504
	ds_read_b128 v[242:245], v213 offset:22528
	ds_read_b128 v[246:249], v213 offset:23552
	global_load_lds_dwordx4 v[198:199], off
	v_lshl_add_u64 v[202:203], s[58:59], 0, v[176:177]
	s_mov_b32 m0, s19
	s_nop 0
	global_load_lds_dwordx4 v[202:203], off
	s_barrier
	s_waitcnt lgkmcnt(0)
	s_waitcnt lgkmcnt(0)
	v_mfma_f32_16x16x32_f16 v[94:97], v[60:63], v[138:141], v[94:97]
	v_mfma_f32_16x16x32_f16 v[68:71], v[78:81], v[138:141], v[70:73]
	v_mfma_f32_16x16x32_f16 v[46:49], v[60:63], v[194:197], v[46:49]
	v_mfma_f32_16x16x32_f16 v[38:41], v[78:81], v[194:197], v[38:41]
	v_mfma_f32_16x16x32_f16 v[30:33], v[60:63], v[234:237], v[30:33]
	v_mfma_f32_16x16x32_f16 v[22:25], v[78:81], v[234:237], v[22:25]
	v_mfma_f32_16x16x32_f16 v[14:17], v[60:63], v[242:245], v[14:17]
	v_mfma_f32_16x16x32_f16 v[6:9], v[78:81], v[242:245], v[6:9]
	v_mfma_f32_16x16x32_f16 v[94:97], v[64:67], v[146:149], v[94:97]
	v_mfma_f32_16x16x32_f16 v[68:71], v[82:85], v[146:149], v[68:71]
	v_mfma_f32_16x16x32_f16 v[46:49], v[64:67], v[226:229], v[46:49]
	v_mfma_f32_16x16x32_f16 v[38:41], v[82:85], v[226:229], v[38:41]
	v_mfma_f32_16x16x32_f16 v[30:33], v[64:67], v[238:241], v[30:33]
	v_mfma_f32_16x16x32_f16 v[22:25], v[82:85], v[238:241], v[22:25]
	v_mfma_f32_16x16x32_f16 v[14:17], v[64:67], v[246:249], v[14:17]
	v_mfma_f32_16x16x32_f16 v[6:9], v[82:85], v[246:249], v[6:9]
	s_barrier
; #define PG8_STAGE(bufoff, gbase, voff) do { _Pragma("unroll") for (int _i = 0; _i < 2; ++_i) \
;         __builtin_amdgcn_global_load_lds((const unsigned*)((const char*)(gbase) + (voff)[_i]), (LAS unsigned*)(lds + (bufoff) + ldsw + _i * 8192), 16, 0, 0); } while (0)
; #define PG8_LDA(dst, b, h) do { _Pragma("unroll") for (int m = 0; m < 4; ++m) _Pragma("unroll") for (int k = 0; k < 2; ++k) dst[m][k] = *(const LAS f16x8*)(lds + PG8_SA(b, h) + aoff + m * 2048 + k * 1024); } while (0)
; #define PG8_LDB(dst, b, h) do { _Pragma("unroll") for (int n = 0; n < 2; ++n) _Pragma("unroll") for (int k = 0; k < 2; ++k) dst[n][k] = *(const LAS f16x8*)(lds + PG8_SB(b, h) + boff + n * 2048 + k * 1024); } while (0)
; #define PG8_MMA(ai, bj, At, Bt) do { __builtin_amdgcn_s_setprio(1); _Pragma("unroll") for (int m = 0; m < 4; ++m) _Pragma("unroll") for (int n = 0; n < 2; ++n) _Pragma("unroll") for (int k = 0; k < 2; ++k) \
;         acc[ai][bj][m][n] = __builtin_amdgcn_mfma_f32_16x16x32_f16(Bt[n][k], At[m][k], acc[ai][bj][m][n], 0, 0, 0); __builtin_amdgcn_s_setprio(0); } while (0)
; #define PG8_WAIT_V(n) asm volatile("s_waitcnt vmcnt(" #n ")" ::: "memory")
; #define PG8_WAIT_L(n) asm volatile("s_waitcnt lgkmcnt(" #n ")" ::: "memory")
; #define PG8_BAR __builtin_amdgcn_s_barrier()
; #define PG8_SCHED __builtin_amdgcn_sched_barrier(0)
; template <class Epi>
; __device__ __forceinline__ void gemm_phase(LAS unsigned char* lds, const Gemm g0, const StaticOrder& S, const Epi& E) {
;     ...
;             PG8_STAGE(PG8_SB(0, 1), b2 + hstep, voffB);
;             PG8_WAIT_V(6); PG8_BAR; PG8_MMA(1, 1, At, B1); PG8_BAR;
;             PG8_LDB(B0, 1, 0); PG8_SCHED; PG8_LDA(At, 1, 0); PG8_STAGE(PG8_SA(0, 1), a2 + hstep, voffA);
;             PG8_WAIT_L(8); PG8_BAR; PG8_WAIT_L(0); PG8_MMA(0, 0, At, B0); PG8_BAR; PG8_SCHED;
	s_add_u32 s22, s52, 0x80000
	s_addc_u32 s23, s53, 0
	s_add_i32 s82, s83, s5
	v_lshl_add_u64 v[60:61], s[22:23], 0, v[178:179]
	s_mov_b32 m0, s82
	s_nop 0
	global_load_lds_dwordx4 v[60:61], off
	v_lshl_add_u64 v[60:61], s[22:23], 0, v[174:175]
	s_add_i32 m0, s82, 0x2000
	s_nop 0
	global_load_lds_dwordx4 v[60:61], off
	s_waitcnt vmcnt(6)
	s_barrier
	v_mfma_f32_16x16x32_f16 v[50:53], v[214:217], v[138:141], v[50:53]
	v_mfma_f32_16x16x32_f16 v[42:45], v[162:165], v[194:197], v[42:45]
	v_mfma_f32_16x16x32_f16 v[34:37], v[214:217], v[194:197], v[34:37]
	v_mfma_f32_16x16x32_f16 v[26:29], v[162:165], v[234:237], v[26:29]
	v_mfma_f32_16x16x32_f16 v[18:21], v[214:217], v[234:237], v[18:21]
	v_mfma_f32_16x16x32_f16 v[10:13], v[162:165], v[242:245], v[10:13]
	v_mfma_f32_16x16x32_f16 v[2:5], v[214:217], v[242:245], v[2:5]
	v_mfma_f32_16x16x32_f16 v[60:63], v[162:165], v[138:141], v[74:77]
	v_mfma_f32_16x16x32_f16 v[50:53], v[170:173], v[146:149], v[50:53]
	v_mfma_f32_16x16x32_f16 v[42:45], v[222:225], v[226:229], v[42:45]
	v_mfma_f32_16x16x32_f16 v[34:37], v[170:173], v[226:229], v[34:37]
	v_mfma_f32_16x16x32_f16 v[26:29], v[222:225], v[238:241], v[26:29]
	v_mfma_f32_16x16x32_f16 v[18:21], v[170:173], v[238:241], v[18:21]
	v_mfma_f32_16x16x32_f16 v[10:13], v[222:225], v[246:249], v[10:13]
	v_mfma_f32_16x16x32_f16 v[2:5], v[170:173], v[246:249], v[2:5]
	v_mfma_f32_16x16x32_f16 v[60:63], v[222:225], v[146:149], v[60:63]
	s_add_i32 s82, 0, 0x18000
	v_add_u32_e32 v72, s82, v189
	s_barrier
	ds_read_b128 v[64:67], v72
	ds_read_b128 v[74:77], v72 offset:1024
	ds_read_b128 v[78:81], v72 offset:2048
	ds_read_b128 v[82:85], v72 offset:3072
	s_add_u32 s22, s58, 0x80000
	s_addc_u32 s23, s59, 0
	s_mov_b32 m0, s28
	v_lshl_add_u64 v[72:73], s[22:23], 0, v[180:181]
	ds_read_b128 v[138:141], v213 offset:32768
	ds_read_b128 v[146:149], v213 offset:33792
	ds_read_b128 v[162:165], v213 offset:34816
	ds_read_b128 v[170:173], v213 offset:35840
	ds_read_b128 v[194:197], v213 offset:36864
	ds_read_b128 v[214:217], v213 offset:37888
	ds_read_b128 v[222:225], v213 offset:38912
	ds_read_b128 v[226:229], v213 offset:39936
	global_load_lds_dwordx4 v[72:73], off
	v_lshl_add_u64 v[72:73], s[22:23], 0, v[176:177]
	s_mov_b32 m0, s29
	s_nop 0
	global_load_lds_dwordx4 v[72:73], off
	s_waitcnt lgkmcnt(8)
	s_barrier
	s_waitcnt lgkmcnt(0)
	s_waitcnt lgkmcnt(0)
	v_mfma_f32_16x16x32_f16 v[158:161], v[64:67], v[138:141], v[158:161]
	v_mfma_f32_16x16x32_f16 v[150:153], v[78:81], v[138:141], v[150:153]
	v_mfma_f32_16x16x32_f16 v[142:145], v[64:67], v[162:165], v[142:145]
	v_mfma_f32_16x16x32_f16 v[134:137], v[78:81], v[162:165], v[134:137]
	v_mfma_f32_16x16x32_f16 v[126:129], v[64:67], v[194:197], v[126:129]
	v_mfma_f32_16x16x32_f16 v[118:121], v[78:81], v[194:197], v[118:121]
	v_mfma_f32_16x16x32_f16 v[110:113], v[64:67], v[222:225], v[110:113]
	v_mfma_f32_16x16x32_f16 v[102:105], v[78:81], v[222:225], v[102:105]
	v_mfma_f32_16x16x32_f16 v[158:161], v[74:77], v[146:149], v[158:161]
	v_mfma_f32_16x16x32_f16 v[150:153], v[82:85], v[146:149], v[150:153]
	v_mfma_f32_16x16x32_f16 v[142:145], v[74:77], v[170:173], v[142:145]
	v_mfma_f32_16x16x32_f16 v[134:137], v[82:85], v[170:173], v[134:137]
	v_mfma_f32_16x16x32_f16 v[126:129], v[74:77], v[214:217], v[126:129]
	v_mfma_f32_16x16x32_f16 v[118:121], v[82:85], v[214:217], v[118:121]
	v_mfma_f32_16x16x32_f16 v[110:113], v[74:77], v[226:229], v[110:113]
	v_mfma_f32_16x16x32_f16 v[102:105], v[82:85], v[226:229], v[102:105]
	s_barrier
	s_add_i32 s58, 0, 0x1c000
	v_add_u32_e32 v72, s58, v189
	s_add_i32 s22, s82, s5
	ds_read_b128 v[234:237], v72
	ds_read_b128 v[238:241], v72 offset:1024
	ds_read_b128 v[242:245], v72 offset:2048
	ds_read_b128 v[246:249], v72 offset:3072
	v_lshl_add_u64 v[72:73], v[186:187], 0, s[64:65]
	s_mov_b32 m0, s22
	s_nop 0
	global_load_lds_dwordx4 v[72:73], off
	v_lshl_add_u64 v[72:73], v[190:191], 0, s[64:65]
	s_add_i32 m0, s22, 0x2000
	s_nop 0
	global_load_lds_dwordx4 v[72:73], off
	s_barrier
; #define PG8_STAGE(bufoff, gbase, voff) do { _Pragma("unroll") for (int _i = 0; _i < 2; ++_i) \
;         __builtin_amdgcn_global_load_lds((const unsigned*)((const char*)(gbase) + (voff)[_i]), (LAS unsigned*)(lds + (bufoff) + ldsw + _i * 8192), 16, 0, 0); } while (0)
; #define PG8_LDA(dst, b, h) do { _Pragma("unroll") for (int m = 0; m < 4; ++m) _Pragma("unroll") for (int k = 0; k < 2; ++k) dst[m][k] = *(const LAS f16x8*)(lds + PG8_SA(b, h) + aoff + m * 2048 + k * 1024); } while (0)
; #define PG8_LDB(dst, b, h) do { _Pragma("unroll") for (int n = 0; n < 2; ++n) _Pragma("unroll") for (int k = 0; k < 2; ++k) dst[n][k] = *(const LAS f16x8*)(lds + PG8_SB(b, h) + boff + n * 2048 + k * 1024); } while (0)
; #define PG8_MMA(ai, bj, At, Bt) do { __builtin_amdgcn_s_setprio(1); _Pragma("unroll") for (int m = 0; m < 4; ++m) _Pragma("unroll") for (int n = 0; n < 2; ++n) _Pragma("unroll") for (int k = 0; k < 2; ++k) \
;         acc[ai][bj][m][n] = __builtin_amdgcn_mfma_f32_16x16x32_f16(Bt[n][k], At[m][k], acc[ai][bj][m][n], 0, 0, 0); __builtin_amdgcn_s_setprio(0); } while (0)
; #define PG8_WAIT_V(n) asm volatile("s_waitcnt vmcnt(" #n ")" ::: "memory")
; #define PG8_WAIT_L(n) asm volatile("s_waitcnt lgkmcnt(" #n ")" ::: "memory")
; #define PG8_BAR __builtin_amdgcn_s_barrier()
; #define PG8_SCHED __builtin_amdgcn_sched_barrier(0)
; template <class Epi>
; __device__ __forceinline__ void gemm_phase(LAS unsigned char* lds, const Gemm g0, const StaticOrder& S, const Epi& E) {
;     ...
;             PG8_LDB(B1, 1, 1); PG8_STAGE(PG8_SB(1, 0), b3, voffB);
;             PG8_BAR; PG8_WAIT_L(0); PG8_MMA(0, 1, At, B1); PG8_BAR;
;             PG8_LDA(At, 1, 1); PG8_STAGE(PG8_SA(1, 0), a3, voffA);
;             PG8_BAR; PG8_WAIT_L(0); PG8_MMA(1, 0, At, B0); PG8_BAR; PG8_SCHED;
;             PG8_STAGE(PG8_SB(1, 1), b3 + hstep, voffB);
;             PG8_WAIT_V(6); PG8_BAR; PG8_MMA(1, 1, At, B1); PG8_BAR;
	s_waitcnt lgkmcnt(0)
	s_waitcnt lgkmcnt(0)
	v_mfma_f32_16x16x32_f16 v[154:157], v[234:237], v[138:141], v[154:157]
	v_mfma_f32_16x16x32_f16 v[86:89], v[242:245], v[138:141], v[86:89]
	v_mfma_f32_16x16x32_f16 v[154:157], v[238:241], v[146:149], v[154:157]
	v_mfma_f32_16x16x32_f16 v[146:149], v[246:249], v[146:149], v[86:89]
	v_mfma_f32_16x16x32_f16 v[86:89], v[234:237], v[162:165], v[90:93]
	v_mfma_f32_16x16x32_f16 v[138:141], v[238:241], v[170:173], v[86:89]
	v_mfma_f32_16x16x32_f16 v[86:89], v[242:245], v[162:165], v[130:133]
	v_mfma_f32_16x16x32_f16 v[130:133], v[246:249], v[170:173], v[86:89]
	v_mfma_f32_16x16x32_f16 v[86:89], v[234:237], v[194:197], v[122:125]
	v_mfma_f32_16x16x32_f16 v[122:125], v[238:241], v[214:217], v[86:89]
	v_mfma_f32_16x16x32_f16 v[86:89], v[242:245], v[194:197], v[114:117]
	v_mfma_f32_16x16x32_f16 v[114:117], v[246:249], v[214:217], v[86:89]
	v_mfma_f32_16x16x32_f16 v[86:89], v[234:237], v[222:225], v[106:109]
	v_mfma_f32_16x16x32_f16 v[106:109], v[238:241], v[226:229], v[86:89]
	v_mfma_f32_16x16x32_f16 v[86:89], v[242:245], v[222:225], v[98:101]
	v_mfma_f32_16x16x32_f16 v[98:101], v[246:249], v[226:229], v[86:89]
	s_mov_b32 m0, s31
	v_lshl_add_u64 v[72:73], v[198:199], 0, s[64:65]
	s_barrier
	s_nop 2
	ds_read_b128 v[86:89], v213 offset:49152
	ds_read_b128 v[90:93], v213 offset:50176
	ds_read_b128 v[162:165], v213 offset:51200
	ds_read_b128 v[170:173], v213 offset:52224
	ds_read_b128 v[194:197], v213 offset:53248
	ds_read_b128 v[214:217], v213 offset:54272
	ds_read_b128 v[222:225], v213 offset:55296
	ds_read_b128 v[226:229], v213 offset:56320
	global_load_lds_dwordx4 v[72:73], off
	v_lshl_add_u64 v[72:73], v[202:203], 0, s[64:65]
	s_mov_b32 m0, s61
	s_nop 0
	global_load_lds_dwordx4 v[72:73], off
	s_barrier
	s_waitcnt lgkmcnt(0)
	s_waitcnt lgkmcnt(0)
	v_mfma_f32_16x16x32_f16 v[94:97], v[64:67], v[86:89], v[94:97]
	v_mfma_f32_16x16x32_f16 v[68:71], v[78:81], v[86:89], v[68:71]
	v_mfma_f32_16x16x32_f16 v[46:49], v[64:67], v[162:165], v[46:49]
	v_mfma_f32_16x16x32_f16 v[38:41], v[78:81], v[162:165], v[38:41]
	v_mfma_f32_16x16x32_f16 v[30:33], v[64:67], v[194:197], v[30:33]
	v_mfma_f32_16x16x32_f16 v[22:25], v[78:81], v[194:197], v[22:25]
	v_mfma_f32_16x16x32_f16 v[14:17], v[64:67], v[222:225], v[14:17]
	v_mfma_f32_16x16x32_f16 v[6:9], v[78:81], v[222:225], v[6:9]
	v_mfma_f32_16x16x32_f16 v[94:97], v[74:77], v[90:93], v[94:97]
	v_mfma_f32_16x16x32_f16 v[70:73], v[82:85], v[90:93], v[68:71]
	v_mfma_f32_16x16x32_f16 v[46:49], v[74:77], v[170:173], v[46:49]
	v_mfma_f32_16x16x32_f16 v[38:41], v[82:85], v[170:173], v[38:41]
	v_mfma_f32_16x16x32_f16 v[30:33], v[74:77], v[214:217], v[30:33]
	v_mfma_f32_16x16x32_f16 v[22:25], v[82:85], v[214:217], v[22:25]
	v_mfma_f32_16x16x32_f16 v[14:17], v[74:77], v[226:229], v[14:17]
	v_mfma_f32_16x16x32_f16 v[6:9], v[82:85], v[226:229], v[6:9]
	s_barrier
	s_add_u32 s22, s52, 0x80080
	s_addc_u32 s23, s53, 0
	s_add_i32 s52, s58, s5
	v_lshl_add_u64 v[64:65], s[22:23], 0, v[178:179]
	s_mov_b32 m0, s52
	s_nop 0
	global_load_lds_dwordx4 v[64:65], off
	v_lshl_add_u64 v[64:65], s[22:23], 0, v[174:175]
	s_add_i32 m0, s52, 0x2000
	s_nop 0
	global_load_lds_dwordx4 v[64:65], off
	s_waitcnt vmcnt(6)
	s_barrier
	v_mfma_f32_16x16x32_f16 v[60:63], v[234:237], v[86:89], v[60:63]
	v_mfma_f32_16x16x32_f16 v[50:53], v[242:245], v[86:89], v[50:53]
	v_mfma_f32_16x16x32_f16 v[42:45], v[234:237], v[162:165], v[42:45]
	v_mfma_f32_16x16x32_f16 v[34:37], v[242:245], v[162:165], v[34:37]
	v_mfma_f32_16x16x32_f16 v[26:29], v[234:237], v[194:197], v[26:29]
	v_mfma_f32_16x16x32_f16 v[18:21], v[242:245], v[194:197], v[18:21]
	v_mfma_f32_16x16x32_f16 v[10:13], v[234:237], v[222:225], v[10:13]
	v_mfma_f32_16x16x32_f16 v[2:5], v[242:245], v[222:225], v[2:5]
	v_mfma_f32_16x16x32_f16 v[74:77], v[238:241], v[90:93], v[60:63]
	v_mfma_f32_16x16x32_f16 v[50:53], v[246:249], v[90:93], v[50:53]
	v_mfma_f32_16x16x32_f16 v[42:45], v[238:241], v[170:173], v[42:45]
	v_mfma_f32_16x16x32_f16 v[34:37], v[246:249], v[170:173], v[34:37]
	v_mfma_f32_16x16x32_f16 v[26:29], v[238:241], v[214:217], v[26:29]
	v_mfma_f32_16x16x32_f16 v[18:21], v[246:249], v[214:217], v[18:21]
	v_mfma_f32_16x16x32_f16 v[10:13], v[238:241], v[226:229], v[10:13]
	v_mfma_f32_16x16x32_f16 v[2:5], v[246:249], v[226:229], v[2:5]
	s_add_i32 s81, s81, 2
	s_add_u32 s24, s24, 0x100
	s_addc_u32 s25, s25, 0
	s_add_u32 s50, s50, 0x100
	s_addc_u32 s51, s51, 0
	s_cmp_gt_u32 s81, 29
	s_barrier
	s_cbranch_scc1 .LBB0_616

; #define PG8_STAGE(bufoff, gbase, voff) do { _Pragma("unroll") for (int _i = 0; _i < 2; ++_i) \
;         __builtin_amdgcn_global_load_lds((const unsigned*)((const char*)(gbase) + (voff)[_i]), (LAS unsigned*)(lds + (bufoff) + ldsw + _i * 8192), 16, 0, 0); } while (0)
; #define PG8_LDA(dst, b, h) do { _Pragma("unroll") for (int m = 0; m < 4; ++m) _Pragma("unroll") for (int k = 0; k < 2; ++k) dst[m][k] = *(const LAS f16x8*)(lds + PG8_SA(b, h) + aoff + m * 2048 + k * 1024); } while (0)
; #define PG8_LDB(dst, b, h) do { _Pragma("unroll") for (int n = 0; n < 2; ++n) _Pragma("unroll") for (int k = 0; k < 2; ++k) dst[n][k] = *(const LAS f16x8*)(lds + PG8_SB(b, h) + boff + n * 2048 + k * 1024); } while (0)
; #define PG8_MMA(ai, bj, At, Bt) do { __builtin_amdgcn_s_setprio(1); _Pragma("unroll") for (int m = 0; m < 4; ++m) _Pragma("unroll") for (int n = 0; n < 2; ++n) _Pragma("unroll") for (int k = 0; k < 2; ++k) \
;         acc[ai][bj][m][n] = __builtin_amdgcn_mfma_f32_16x16x32_f16(Bt[n][k], At[m][k], acc[ai][bj][m][n], 0, 0, 0); __builtin_amdgcn_s_setprio(0); } while (0)
; #define PG8_WAIT_L(n) asm volatile("s_waitcnt lgkmcnt(" #n ")" ::: "memory")
; #define PG8_BAR __builtin_amdgcn_s_barrier()
; #define PG8_SCHED __builtin_amdgcn_sched_barrier(0)
; template <class Epi>
; __device__ __forceinline__ void gemm_phase(LAS unsigned char* lds, const Gemm g0, const StaticOrder& S, const Epi& E) {
;     ...
;             PG8_LDB(B0, 0, 0); PG8_SCHED; PG8_LDA(At, 0, 0); PG8_STAGE(PG8_SA(1, 1), a1 + hstep, voffA);
;             PG8_WAIT_L(8); PG8_BAR; PG8_WAIT_L(0); PG8_MMA(0, 0, At, B0); PG8_BAR; PG8_SCHED;
;             PG8_LDB(B1, 0, 1); PG8_STAGE(PG8_SB(0, 0), b2, voffB);
;             PG8_BAR; PG8_WAIT_L(0); PG8_MMA(0, 1, At, B1); PG8_BAR;
;             PG8_LDA(At, 0, 1); PG8_STAGE(PG8_SA(0, 0), a2, voffA);
;             PG8_BAR; PG8_WAIT_L(0); PG8_MMA(1, 0, At, B0); PG8_BAR; PG8_SCHED;
.LBB0_672:
	s_add_u32 s10, s12, 0x100
	s_addc_u32 s11, s13, 0
	s_add_i32 s23, 0, 0x10000
	v_add_u32_e32 v142, s23, v203
	ds_read_b128 v[130:133], v142
	ds_read_b128 v[134:137], v142 offset:1024
	ds_read_b128 v[138:141], v142 offset:2048
	ds_read_b128 v[142:145], v142 offset:3072
	s_cmpk_eq_i32 s22, 0x54
	s_cselect_b32 s81, s1, s11
	s_cselect_b32 s80, s0, s10
	s_cselect_b32 s63, s59, s25
	s_cselect_b32 s62, s58, s24
	v_lshl_add_u64 v[196:197], s[12:13], 0, v[182:183]
	s_add_i32 m0, s28, 0xc000
	ds_read_b128 v[146:149], v208
	ds_read_b128 v[150:153], v208 offset:1024
	ds_read_b128 v[154:157], v208 offset:2048
	ds_read_b128 v[162:165], v208 offset:3072
	ds_read_b128 v[170:173], v208 offset:4096
	ds_read_b128 v[184:187], v208 offset:5120
	ds_read_b128 v[188:191], v208 offset:6144
	ds_read_b128 v[192:195], v208 offset:7168
	global_load_lds_dwordx4 v[196:197], off
	v_lshl_add_u64 v[196:197], s[12:13], 0, v[180:181]
	s_add_i32 m0, s28, 0xe000
	s_nop 0
	global_load_lds_dwordx4 v[196:197], off
	s_waitcnt lgkmcnt(8)
	s_barrier
	s_waitcnt lgkmcnt(0)
	s_waitcnt lgkmcnt(0)
	v_mfma_f32_16x16x32_f16 v[126:129], v[130:133], v[146:149], v[126:129]
	v_mfma_f32_16x16x32_f16 v[122:125], v[138:141], v[146:149], v[122:125]
	v_mfma_f32_16x16x32_f16 v[110:113], v[130:133], v[154:157], v[110:113]
	v_mfma_f32_16x16x32_f16 v[106:109], v[138:141], v[154:157], v[106:109]
	v_mfma_f32_16x16x32_f16 v[94:97], v[130:133], v[170:173], v[94:97]
	v_mfma_f32_16x16x32_f16 v[90:93], v[138:141], v[170:173], v[90:93]
	v_mfma_f32_16x16x32_f16 v[78:81], v[130:133], v[188:191], v[78:81]
	v_mfma_f32_16x16x32_f16 v[74:77], v[138:141], v[188:191], v[74:77]
	v_mfma_f32_16x16x32_f16 v[126:129], v[134:137], v[150:153], v[126:129]
	v_mfma_f32_16x16x32_f16 v[122:125], v[142:145], v[150:153], v[122:125]
	v_mfma_f32_16x16x32_f16 v[110:113], v[134:137], v[162:165], v[110:113]
	v_mfma_f32_16x16x32_f16 v[106:109], v[142:145], v[162:165], v[106:109]
	v_mfma_f32_16x16x32_f16 v[94:97], v[134:137], v[184:187], v[94:97]
	v_mfma_f32_16x16x32_f16 v[90:93], v[142:145], v[184:187], v[90:93]
	v_mfma_f32_16x16x32_f16 v[78:81], v[134:137], v[192:195], v[78:81]
	v_mfma_f32_16x16x32_f16 v[74:77], v[142:145], v[192:195], v[74:77]
	s_barrier
	s_add_i32 s90, 0, 0x14000
	v_add_u32_e32 v200, s90, v203
	s_add_i32 s12, s23, s19
	ds_read_b128 v[196:199], v200
	ds_read_b128 v[210:213], v200 offset:1024
	ds_read_b128 v[214:217], v200 offset:2048
	ds_read_b128 v[222:225], v200 offset:3072
	v_lshl_add_u64 v[200:201], s[62:63], 0, v[174:175]
	s_mov_b32 m0, s12
	v_lshl_add_u64 v[218:219], s[62:63], 0, v[158:159]
	global_load_lds_dwordx4 v[200:201], off
	s_add_i32 m0, s12, 0x2000
	s_nop 0
	global_load_lds_dwordx4 v[218:219], off
	s_barrier
	s_waitcnt lgkmcnt(0)
	s_waitcnt lgkmcnt(0)
	v_mfma_f32_16x16x32_f16 v[118:121], v[196:199], v[146:149], v[118:121]
	v_mfma_f32_16x16x32_f16 v[114:117], v[214:217], v[146:149], v[114:117]
	v_mfma_f32_16x16x32_f16 v[102:105], v[196:199], v[154:157], v[102:105]
	v_mfma_f32_16x16x32_f16 v[98:101], v[214:217], v[154:157], v[98:101]
	v_mfma_f32_16x16x32_f16 v[86:89], v[196:199], v[170:173], v[86:89]
	v_mfma_f32_16x16x32_f16 v[82:85], v[214:217], v[170:173], v[82:85]
	v_mfma_f32_16x16x32_f16 v[70:73], v[196:199], v[188:191], v[70:73]
	v_mfma_f32_16x16x32_f16 v[66:69], v[214:217], v[188:191], v[66:69]
	v_mfma_f32_16x16x32_f16 v[118:121], v[210:213], v[150:153], v[118:121]
	v_mfma_f32_16x16x32_f16 v[114:117], v[222:225], v[150:153], v[114:117]
	v_mfma_f32_16x16x32_f16 v[102:105], v[210:213], v[162:165], v[102:105]
	v_mfma_f32_16x16x32_f16 v[98:101], v[222:225], v[162:165], v[98:101]
	v_mfma_f32_16x16x32_f16 v[86:89], v[210:213], v[184:187], v[86:89]
	v_mfma_f32_16x16x32_f16 v[82:85], v[222:225], v[184:187], v[82:85]
	v_mfma_f32_16x16x32_f16 v[70:73], v[210:213], v[192:195], v[70:73]
	v_mfma_f32_16x16x32_f16 v[66:69], v[222:225], v[192:195], v[66:69]
	s_mov_b32 m0, s28
	v_lshl_add_u64 v[226:227], s[80:81], 0, v[176:177]
	s_barrier
	ds_read_b128 v[146:149], v208 offset:16384
	ds_read_b128 v[150:153], v208 offset:17408
	ds_read_b128 v[154:157], v208 offset:18432
	ds_read_b128 v[162:165], v208 offset:19456
	ds_read_b128 v[170:173], v208 offset:20480
	ds_read_b128 v[184:187], v208 offset:21504
	ds_read_b128 v[188:191], v208 offset:22528
	ds_read_b128 v[192:195], v208 offset:23552
	global_load_lds_dwordx4 v[226:227], off
	v_lshl_add_u64 v[228:229], s[80:81], 0, v[160:161]
	s_mov_b32 m0, s29
	s_nop 0
	global_load_lds_dwordx4 v[228:229], off
	s_barrier
	s_waitcnt lgkmcnt(0)
	s_waitcnt lgkmcnt(0)
	v_mfma_f32_16x16x32_f16 v[62:65], v[130:133], v[146:149], v[62:65]
	v_mfma_f32_16x16x32_f16 v[58:61], v[138:141], v[146:149], v[58:61]
	v_mfma_f32_16x16x32_f16 v[46:49], v[130:133], v[154:157], v[46:49]
	v_mfma_f32_16x16x32_f16 v[42:45], v[138:141], v[154:157], v[42:45]
	v_mfma_f32_16x16x32_f16 v[30:33], v[130:133], v[170:173], v[30:33]
	v_mfma_f32_16x16x32_f16 v[26:29], v[138:141], v[170:173], v[26:29]
	v_mfma_f32_16x16x32_f16 v[14:17], v[130:133], v[188:191], v[14:17]
	v_mfma_f32_16x16x32_f16 v[10:13], v[138:141], v[188:191], v[10:13]
	v_mfma_f32_16x16x32_f16 v[62:65], v[134:137], v[150:153], v[62:65]
	v_mfma_f32_16x16x32_f16 v[58:61], v[142:145], v[150:153], v[58:61]
	v_mfma_f32_16x16x32_f16 v[46:49], v[134:137], v[162:165], v[46:49]
	v_mfma_f32_16x16x32_f16 v[42:45], v[142:145], v[162:165], v[42:45]
	v_mfma_f32_16x16x32_f16 v[30:33], v[134:137], v[184:187], v[30:33]
	v_mfma_f32_16x16x32_f16 v[26:29], v[142:145], v[184:187], v[26:29]
	v_mfma_f32_16x16x32_f16 v[14:17], v[134:137], v[192:195], v[14:17]
	v_mfma_f32_16x16x32_f16 v[10:13], v[142:145], v[192:195], v[10:13]
	s_barrier
; #define PG8_STAGE(bufoff, gbase, voff) do { _Pragma("unroll") for (int _i = 0; _i < 2; ++_i) \
;         __builtin_amdgcn_global_load_lds((const unsigned*)((const char*)(gbase) + (voff)[_i]), (LAS unsigned*)(lds + (bufoff) + ldsw + _i * 8192), 16, 0, 0); } while (0)
; #define PG8_LDA(dst, b, h) do { _Pragma("unroll") for (int m = 0; m < 4; ++m) _Pragma("unroll") for (int k = 0; k < 2; ++k) dst[m][k] = *(const LAS f16x8*)(lds + PG8_SA(b, h) + aoff + m * 2048 + k * 1024); } while (0)
; #define PG8_LDB(dst, b, h) do { _Pragma("unroll") for (int n = 0; n < 2; ++n) _Pragma("unroll") for (int k = 0; k < 2; ++k) dst[n][k] = *(const LAS f16x8*)(lds + PG8_SB(b, h) + boff + n * 2048 + k * 1024); } while (0)
; #define PG8_MMA(ai, bj, At, Bt) do { __builtin_amdgcn_s_setprio(1); _Pragma("unroll") for (int m = 0; m < 4; ++m) _Pragma("unroll") for (int n = 0; n < 2; ++n) _Pragma("unroll") for (int k = 0; k < 2; ++k) \
;         acc[ai][bj][m][n] = __builtin_amdgcn_mfma_f32_16x16x32_f16(Bt[n][k], At[m][k], acc[ai][bj][m][n], 0, 0, 0); __builtin_amdgcn_s_setprio(0); } while (0)
; #define PG8_WAIT_V(n) asm volatile("s_waitcnt vmcnt(" #n ")" ::: "memory")
; #define PG8_WAIT_L(n) asm volatile("s_waitcnt lgkmcnt(" #n ")" ::: "memory")
; #define PG8_BAR __builtin_amdgcn_s_barrier()
; #define PG8_SCHED __builtin_amdgcn_sched_barrier(0)
; template <class Epi>
; __device__ __forceinline__ void gemm_phase(LAS unsigned char* lds, const Gemm g0, const StaticOrder& S, const Epi& E) {
;     ...
;             PG8_STAGE(PG8_SB(0, 1), b2 + hstep, voffB);
;             PG8_WAIT_V(6); PG8_BAR; PG8_MMA(1, 1, At, B1); PG8_BAR;
;             PG8_LDB(B0, 1, 0); PG8_SCHED; PG8_LDA(At, 1, 0); PG8_STAGE(PG8_SA(0, 1), a2 + hstep, voffA);
;             PG8_WAIT_L(8); PG8_BAR; PG8_WAIT_L(0); PG8_MMA(0, 0, At, B0); PG8_BAR; PG8_SCHED;
	s_add_u32 s12, s62, 0x160000
	s_addc_u32 s13, s63, 0
	s_add_i32 s23, s90, s19
	v_lshl_add_u64 v[130:131], s[12:13], 0, v[174:175]
	s_mov_b32 m0, s23
	s_nop 0
	global_load_lds_dwordx4 v[130:131], off
	v_lshl_add_u64 v[130:131], s[12:13], 0, v[158:159]
	s_add_i32 m0, s23, 0x2000
	s_nop 0
	global_load_lds_dwordx4 v[130:131], off
	s_waitcnt vmcnt(6)
	s_barrier
	v_mfma_f32_16x16x32_f16 v[54:57], v[196:199], v[146:149], v[54:57]
	v_mfma_f32_16x16x32_f16 v[50:53], v[214:217], v[146:149], v[50:53]
	v_mfma_f32_16x16x32_f16 v[38:41], v[196:199], v[154:157], v[38:41]
	v_mfma_f32_16x16x32_f16 v[34:37], v[214:217], v[154:157], v[34:37]
	v_mfma_f32_16x16x32_f16 v[22:25], v[196:199], v[170:173], v[22:25]
	v_mfma_f32_16x16x32_f16 v[18:21], v[214:217], v[170:173], v[18:21]
	v_mfma_f32_16x16x32_f16 v[6:9], v[196:199], v[188:191], v[6:9]
	v_mfma_f32_16x16x32_f16 v[2:5], v[214:217], v[188:191], v[2:5]
	v_mfma_f32_16x16x32_f16 v[54:57], v[210:213], v[150:153], v[54:57]
	v_mfma_f32_16x16x32_f16 v[50:53], v[222:225], v[150:153], v[50:53]
	v_mfma_f32_16x16x32_f16 v[38:41], v[210:213], v[162:165], v[38:41]
	v_mfma_f32_16x16x32_f16 v[34:37], v[222:225], v[162:165], v[34:37]
	v_mfma_f32_16x16x32_f16 v[22:25], v[210:213], v[184:187], v[22:25]
	v_mfma_f32_16x16x32_f16 v[18:21], v[222:225], v[184:187], v[18:21]
	v_mfma_f32_16x16x32_f16 v[6:9], v[210:213], v[192:195], v[6:9]
	v_mfma_f32_16x16x32_f16 v[2:5], v[222:225], v[192:195], v[2:5]
	s_add_i32 s23, 0, 0x18000
	v_add_u32_e32 v142, s23, v203
	s_barrier
	ds_read_b128 v[130:133], v142
	ds_read_b128 v[134:137], v142 offset:1024
	ds_read_b128 v[138:141], v142 offset:2048
	ds_read_b128 v[142:145], v142 offset:3072
	s_add_u32 s12, s80, 0x160000
	s_addc_u32 s13, s81, 0
	s_mov_b32 m0, s31
	v_lshl_add_u64 v[196:197], s[12:13], 0, v[176:177]
	ds_read_b128 v[146:149], v208 offset:32768
	ds_read_b128 v[150:153], v208 offset:33792
	ds_read_b128 v[154:157], v208 offset:34816
	ds_read_b128 v[162:165], v208 offset:35840
	ds_read_b128 v[170:173], v208 offset:36864
	ds_read_b128 v[184:187], v208 offset:37888
	ds_read_b128 v[188:191], v208 offset:38912
	ds_read_b128 v[192:195], v208 offset:39936
	global_load_lds_dwordx4 v[196:197], off
	v_lshl_add_u64 v[196:197], s[12:13], 0, v[160:161]
	s_mov_b32 m0, s61
	s_nop 0
	global_load_lds_dwordx4 v[196:197], off
	s_waitcnt lgkmcnt(8)
	s_barrier
	s_waitcnt lgkmcnt(0)
	s_waitcnt lgkmcnt(0)
	v_mfma_f32_16x16x32_f16 v[126:129], v[130:133], v[146:149], v[126:129]
	v_mfma_f32_16x16x32_f16 v[122:125], v[138:141], v[146:149], v[122:125]
	v_mfma_f32_16x16x32_f16 v[110:113], v[130:133], v[154:157], v[110:113]
	v_mfma_f32_16x16x32_f16 v[106:109], v[138:141], v[154:157], v[106:109]
	v_mfma_f32_16x16x32_f16 v[94:97], v[130:133], v[170:173], v[94:97]
	v_mfma_f32_16x16x32_f16 v[90:93], v[138:141], v[170:173], v[90:93]
	v_mfma_f32_16x16x32_f16 v[78:81], v[130:133], v[188:191], v[78:81]
	v_mfma_f32_16x16x32_f16 v[74:77], v[138:141], v[188:191], v[74:77]
	v_mfma_f32_16x16x32_f16 v[126:129], v[134:137], v[150:153], v[126:129]
	v_mfma_f32_16x16x32_f16 v[122:125], v[142:145], v[150:153], v[122:125]
	v_mfma_f32_16x16x32_f16 v[110:113], v[134:137], v[162:165], v[110:113]
	v_mfma_f32_16x16x32_f16 v[106:109], v[142:145], v[162:165], v[106:109]
	v_mfma_f32_16x16x32_f16 v[94:97], v[134:137], v[184:187], v[94:97]
	v_mfma_f32_16x16x32_f16 v[90:93], v[142:145], v[184:187], v[90:93]
	v_mfma_f32_16x16x32_f16 v[78:81], v[134:137], v[192:195], v[78:81]
	v_mfma_f32_16x16x32_f16 v[74:77], v[142:145], v[192:195], v[74:77]
	s_barrier
	s_add_i32 s80, 0, 0x1c000
	s_add_i32 s12, s23, s19
	v_add_u32_e32 v209, s80, v203
	v_lshl_add_u64 v[200:201], v[200:201], 0, s[64:65]
	s_mov_b32 m0, s12
	ds_read_b128 v[196:199], v209
	ds_read_b128 v[210:213], v209 offset:1024
	ds_read_b128 v[214:217], v209 offset:2048
	ds_read_b128 v[222:225], v209 offset:3072
	global_load_lds_dwordx4 v[200:201], off
	v_lshl_add_u64 v[200:201], v[218:219], 0, s[64:65]
	s_add_i32 m0, s12, 0x2000
	s_nop 0
	global_load_lds_dwordx4 v[200:201], off
	s_barrier
; #define LAS __attribute__((address_space(3)))
; #define GAS __attribute__((address_space(1)))
; #define PG8_STAGE(bufoff, gbase, voff) do { _Pragma("unroll") for (int _i = 0; _i < 2; ++_i) \
;         __builtin_amdgcn_global_load_lds((const unsigned*)((const char*)(gbase) + (voff)[_i]), (LAS unsigned*)(lds + (bufoff) + ldsw + _i * 8192), 16, 0, 0); } while (0)
; #define PG8_LDA(dst, b, h) do { _Pragma("unroll") for (int m = 0; m < 4; ++m) _Pragma("unroll") for (int k = 0; k < 2; ++k) dst[m][k] = *(const LAS f16x8*)(lds + PG8_SA(b, h) + aoff + m * 2048 + k * 1024); } while (0)
; #define PG8_LDB(dst, b, h) do { _Pragma("unroll") for (int n = 0; n < 2; ++n) _Pragma("unroll") for (int k = 0; k < 2; ++k) dst[n][k] = *(const LAS f16x8*)(lds + PG8_SB(b, h) + boff + n * 2048 + k * 1024); } while (0)
; #define PG8_WAIT_V(n) asm volatile("s_waitcnt vmcnt(" #n ")" ::: "memory")
; #define PG8_WAIT_L(n) asm volatile("s_waitcnt lgkmcnt(" #n ")" ::: "memory")
; #define PG8_BAR __builtin_amdgcn_s_barrier()
; #define PG8_SCHED __builtin_amdgcn_sched_barrier(0)
;     __device__ __forceinline__ void operator()(f32x4 (&acc)[2][2][4][2], const Unit& u, int wr, int wc, int fr, int fq) const {
;         const int row0 = u.pm * BM + wr * 64 + fr, colb = u.pn * BM + wc * 32 + 8 * fq;
;         const bool hasln = pstats != nullptr, haszh = zh != nullptr;
;         LAS float* slot = vl + (wr * 4 + wc) * 256;
;         f32x4 rn[2][2]; float ssm[8], ssq[8]; f32x2 stn = {0.f, 0.f};
;         { const int lane = fr + 16 * fq, cL = u.pn * BM + wc * 32 + (lane < 32 ? lane : 96 + lane);
;           float vg = 0.f, vb = 0.f, vt = 0.f;
;           if (hasln) { vg = *(const GAS float*)(pg + cL); vb = *(const GAS float*)(pb + cL); }
;           if (haszh) vt = *(const GAS float*)(tg + cL);
; template <class Epi>
; __device__ __forceinline__ void gemm_phase(LAS unsigned char* lds, const Gemm g0, const StaticOrder& S, const Epi& E) {
;     ...
;             PG8_LDB(B1, 1, 1); PG8_STAGE(PG8_SB(1, 0), b3, voffB);
;             PG8_BAR; PG8_WAIT_L(0); PG8_MMA(0, 1, At, B1); PG8_BAR;
;             PG8_LDA(At, 1, 1); PG8_STAGE(PG8_SA(1, 0), a3, voffA);
;             PG8_BAR; PG8_WAIT_L(0); PG8_MMA(1, 0, At, B0); PG8_BAR; PG8_SCHED;
;             PG8_STAGE(PG8_SB(1, 1), b3 + hstep, voffB);
;             PG8_WAIT_V(6); PG8_BAR; PG8_MMA(1, 1, At, B1); PG8_BAR;
	s_waitcnt lgkmcnt(0)
	s_waitcnt lgkmcnt(0)
	v_mfma_f32_16x16x32_f16 v[118:121], v[196:199], v[146:149], v[118:121]
	v_mfma_f32_16x16x32_f16 v[114:117], v[214:217], v[146:149], v[114:117]
	v_mfma_f32_16x16x32_f16 v[102:105], v[196:199], v[154:157], v[102:105]
	v_mfma_f32_16x16x32_f16 v[98:101], v[214:217], v[154:157], v[98:101]
	v_mfma_f32_16x16x32_f16 v[86:89], v[196:199], v[170:173], v[86:89]
	v_mfma_f32_16x16x32_f16 v[82:85], v[214:217], v[170:173], v[82:85]
	v_mfma_f32_16x16x32_f16 v[70:73], v[196:199], v[188:191], v[70:73]
	v_mfma_f32_16x16x32_f16 v[66:69], v[214:217], v[188:191], v[66:69]
	v_mfma_f32_16x16x32_f16 v[118:121], v[210:213], v[150:153], v[118:121]
	v_mfma_f32_16x16x32_f16 v[114:117], v[222:225], v[150:153], v[114:117]
	v_mfma_f32_16x16x32_f16 v[102:105], v[210:213], v[162:165], v[102:105]
	v_mfma_f32_16x16x32_f16 v[98:101], v[222:225], v[162:165], v[98:101]
	v_mfma_f32_16x16x32_f16 v[86:89], v[210:213], v[184:187], v[86:89]
	v_mfma_f32_16x16x32_f16 v[82:85], v[222:225], v[184:187], v[82:85]
	v_mfma_f32_16x16x32_f16 v[70:73], v[210:213], v[192:195], v[70:73]
	v_mfma_f32_16x16x32_f16 v[66:69], v[222:225], v[192:195], v[66:69]
	s_mov_b32 m0, s83
	v_lshl_add_u64 v[200:201], v[226:227], 0, s[64:65]
	s_barrier
	ds_read_b128 v[146:149], v208 offset:49152
	ds_read_b128 v[150:153], v208 offset:50176
	ds_read_b128 v[154:157], v208 offset:51200
	ds_read_b128 v[162:165], v208 offset:52224
	ds_read_b128 v[170:173], v208 offset:53248
	ds_read_b128 v[184:187], v208 offset:54272
	ds_read_b128 v[188:191], v208 offset:55296
	ds_read_b128 v[192:195], v208 offset:56320
	global_load_lds_dwordx4 v[200:201], off
	v_lshl_add_u64 v[200:201], v[228:229], 0, s[64:65]
	s_mov_b32 m0, s84
	s_nop 0
	global_load_lds_dwordx4 v[200:201], off
	s_barrier
	s_waitcnt lgkmcnt(0)
	s_waitcnt lgkmcnt(0)
	v_mfma_f32_16x16x32_f16 v[62:65], v[130:133], v[146:149], v[62:65]
	v_mfma_f32_16x16x32_f16 v[58:61], v[138:141], v[146:149], v[58:61]
	v_mfma_f32_16x16x32_f16 v[46:49], v[130:133], v[154:157], v[46:49]
	v_mfma_f32_16x16x32_f16 v[42:45], v[138:141], v[154:157], v[42:45]
	v_mfma_f32_16x16x32_f16 v[30:33], v[130:133], v[170:173], v[30:33]
	v_mfma_f32_16x16x32_f16 v[26:29], v[138:141], v[170:173], v[26:29]
	v_mfma_f32_16x16x32_f16 v[14:17], v[130:133], v[188:191], v[14:17]
	v_mfma_f32_16x16x32_f16 v[10:13], v[138:141], v[188:191], v[10:13]
	v_mfma_f32_16x16x32_f16 v[62:65], v[134:137], v[150:153], v[62:65]
	v_mfma_f32_16x16x32_f16 v[58:61], v[142:145], v[150:153], v[58:61]
	v_mfma_f32_16x16x32_f16 v[46:49], v[134:137], v[162:165], v[46:49]
	v_mfma_f32_16x16x32_f16 v[42:45], v[142:145], v[162:165], v[42:45]
	v_mfma_f32_16x16x32_f16 v[30:33], v[134:137], v[184:187], v[30:33]
	v_mfma_f32_16x16x32_f16 v[26:29], v[142:145], v[184:187], v[26:29]
	v_mfma_f32_16x16x32_f16 v[14:17], v[134:137], v[192:195], v[14:17]
	v_mfma_f32_16x16x32_f16 v[10:13], v[142:145], v[192:195], v[10:13]
	s_barrier
	s_add_u32 s12, s62, 0x160080
	s_addc_u32 s13, s63, 0
	s_add_i32 s23, s80, s19
	v_lshl_add_u64 v[130:131], s[12:13], 0, v[174:175]
	s_mov_b32 m0, s23
	s_nop 0
	global_load_lds_dwordx4 v[130:131], off
	v_lshl_add_u64 v[130:131], s[12:13], 0, v[158:159]
	s_add_i32 m0, s23, 0x2000
	s_nop 0
	global_load_lds_dwordx4 v[130:131], off
	s_waitcnt vmcnt(6)
	s_barrier
	v_mfma_f32_16x16x32_f16 v[54:57], v[196:199], v[146:149], v[54:57]
	v_mfma_f32_16x16x32_f16 v[50:53], v[214:217], v[146:149], v[50:53]
	v_mfma_f32_16x16x32_f16 v[38:41], v[196:199], v[154:157], v[38:41]
	v_mfma_f32_16x16x32_f16 v[34:37], v[214:217], v[154:157], v[34:37]
	v_mfma_f32_16x16x32_f16 v[22:25], v[196:199], v[170:173], v[22:25]
	v_mfma_f32_16x16x32_f16 v[18:21], v[214:217], v[170:173], v[18:21]
	v_mfma_f32_16x16x32_f16 v[6:9], v[196:199], v[188:191], v[6:9]
	v_mfma_f32_16x16x32_f16 v[2:5], v[214:217], v[188:191], v[2:5]
	v_mfma_f32_16x16x32_f16 v[54:57], v[210:213], v[150:153], v[54:57]
	v_mfma_f32_16x16x32_f16 v[50:53], v[222:225], v[150:153], v[50:53]
	v_mfma_f32_16x16x32_f16 v[38:41], v[210:213], v[162:165], v[38:41]
	v_mfma_f32_16x16x32_f16 v[34:37], v[222:225], v[162:165], v[34:37]
	v_mfma_f32_16x16x32_f16 v[22:25], v[210:213], v[184:187], v[22:25]
	v_mfma_f32_16x16x32_f16 v[18:21], v[222:225], v[184:187], v[18:21]
	v_mfma_f32_16x16x32_f16 v[6:9], v[210:213], v[192:195], v[6:9]
	v_mfma_f32_16x16x32_f16 v[2:5], v[222:225], v[192:195], v[2:5]
	s_add_i32 s22, s22, 2
	s_add_u32 s24, s24, 0x100
	s_addc_u32 s25, s25, 0
	s_cmpk_gt_u32 s22, 0x55
	s_mov_b64 s[12:13], s[10:11]
	s_barrier
	s_cbranch_scc0 .LBB0_672
	s_lshl_b32 s10, s92, 8
	s_or_b32 s12, s10, s82
	v_add_u32_e32 v130, s12, v204
	v_ashrrev_i32_e32 v131, 31, v130
	v_lshlrev_b64 v[132:133], 2, v[130:131]
	v_lshl_add_u64 v[134:135], s[38:39], 0, v[132:133]
	v_lshl_add_u64 v[132:133], s[48:49], 0, v[132:133]
	global_load_dword v146, v[134:135], off
	global_load_dword v147, v[132:133], off
	v_readlane_b32 s22, v254, 55
	v_readlane_b32 s23, v254, 56
	s_andn2_b64 vcc, exec, s[22:23]
	v_mov_b32_e32 v148, 0
	v_cndmask_b32_e64 v132, 0, 1, s[22:23]
	v_cmp_ne_u32_e64 s[10:11], 1, v132
	s_cbranch_vccnz .LBB0_675
	v_lshl_add_u64 v[130:131], v[130:131], 2, s[50:51]
	global_load_dword v148, v[130:131], off
